# v19: v9 + prompt-attention V^T image staged by LDS-DMA loads issued right after the K-image barrier (overlaps the softmax) instead of global loads and ds_write after it
# speedup vs baseline: 1.0012x; 1.0012x over previous
; #define LAS __attribute__((address_space(3)))
; DI void attn_prompt_item(const Params& p, int item, ldsp lds, int tid_) {
;     ...
;   const int wid = __builtin_amdgcn_readfirstlane(tid >> 6), lane = tid & 63, l31 = lane & 31, h2 = lane >> 5;
;   const int b = item >> 5, h = (item >> 3) & 3, qt = item & 7;
;   bf16_t* qx = (bf16_t*)(p.ws + B_QX);
;   const bf16_t* mkb = (const bf16_t*)(p.ws + B_MKB);
;   const bf16_t* mvt = (const bf16_t*)(p.ws + B_MVT);
;   const size_t qrow = (size_t)b * 2048 + qt * 256 + wid * 32 + l31;
;   bf16x8 qreg[8];
; #pragma unroll
;   for (int s = 0; s < 8; ++s) qreg[s] = *(const bf16x8*)(qx + qrow * D + h * 256 + 16 * s + 8 * h2);
; #pragma unroll
;   for (int hb = 0; hb < 2; ++hb) {
;     u32x4 kp[8];
; #pragma unroll
;     for (int i = 0; i < 8; ++i) { const int idx = tid + 512 * (hb * 8 + i), key = idx >> 5, c = idx & 31; kp[i] = ld16(mkb + (size_t)(b * 256 + key) * D + h * 256 + c * 8); }
; #pragma unroll
;     for (int i = 0; i < 8; ++i) { const int idx = tid + 512 * (hb * 8 + i), key = idx >> 5, c = idx & 31; *(LAS u32x4*)(lds + key * 512 + ((c ^ (key & 15)) * 16)) = kp[i]; }
.LBB0_1672:
	v_mov_b32_e32 v68, v212
	s_ashr_i32 s28, s45, 5
	s_ashr_i32 s29, s28, 31
	v_readfirstlane_b32 s3, v68
	s_lshl_b64 s[46:47], s[28:29], 11
	s_and_b32 s26, s33, 0x700
	s_ashr_i32 s3, s3, 1
	v_and_b32_e32 v69, 31, v68
	s_or_b32 s26, s46, s26
	s_and_b32 s48, s3, 0xffffffe0
	s_ashr_i32 s49, s48, 31
	v_or_b32_e32 v0, s26, v69
	v_mov_b32_e32 v1, s47
	s_and_b32 s3, s30, 0x300
	v_add_u32_e32 v6, 0x200, v68
	v_lshl_add_u64 v[0:1], v[0:1], 0, s[48:49]
	s_lshl_b32 s26, s3, 1
	s_lshl_b32 s29, s28, 8
	v_ashrrev_i32_e32 v176, 5, v68
	v_ashrrev_i32_e32 v177, 5, v6
	v_lshlrev_b64 v[162:163], 11, v[0:1]
	s_add_u32 s46, s0, s26
	v_lshlrev_b32_e32 v174, 4, v68
	v_add_u32_e32 v4, s29, v176
	v_add_u32_e32 v6, s29, v177
	v_bfe_u32 v208, v68, 5, 1
	v_lshl_add_u64 v[0:1], s[4:5], 0, v[162:163]
	s_addc_u32 s47, s1, 0
	v_and_b32_e32 v164, 0x1f0, v174
	v_mov_b32_e32 v165, v161
	v_ashrrev_i32_e32 v5, 31, v4
	v_ashrrev_i32_e32 v7, 31, v6
	v_lshl_add_u64 v[0:1], v[0:1], 0, s[26:27]
	v_lshlrev_b32_e32 v2, 4, v208
	v_mov_b32_e32 v3, v161
	v_lshl_add_u64 v[64:65], s[46:47], 0, v[164:165]
	v_lshlrev_b64 v[4:5], 11, v[4:5]
	v_lshlrev_b64 v[6:7], 11, v[6:7]
	v_lshl_add_u64 v[166:167], v[0:1], 0, v[2:3]
	v_lshl_add_u64 v[4:5], v[64:65], 0, v[4:5]
	v_lshl_add_u64 v[8:9], v[64:65], 0, v[6:7]
	global_load_dwordx4 v[0:3], v[166:167], off
	global_load_dwordx4 v[152:155], v[166:167], off offset:32
	global_load_dwordx4 v[148:151], v[166:167], off offset:64
	global_load_dwordx4 v[144:147], v[166:167], off offset:96
	global_load_dwordx4 v[140:143], v[166:167], off offset:128
	global_load_dwordx4 v[136:139], v[166:167], off offset:160
	global_load_dwordx4 v[132:135], v[166:167], off offset:192
	global_load_dwordx4 v[128:131], v[166:167], off offset:224
	s_nop 0
	global_load_dwordx4 v[4:7], v[4:5], off
	s_nop 0
	global_load_dwordx4 v[8:11], v[8:9], off
	v_add_u32_e32 v12, 0x400, v68
	v_add_u32_e32 v14, 0x600, v68
	v_add_u32_e32 v20, 0x800, v68
	v_add_u32_e32 v22, 0xa00, v68
	v_ashrrev_i32_e32 v178, 5, v12
	v_ashrrev_i32_e32 v180, 5, v14
	v_ashrrev_i32_e32 v181, 5, v20
	v_ashrrev_i32_e32 v183, 5, v22
	v_add_u32_e32 v28, 0xc00, v68
	v_add_u32_e32 v30, 0xe00, v68
	v_add_u32_e32 v36, 0x1000, v68
	v_add_u32_e32 v38, 0x1200, v68
	v_add_u32_e32 v44, 0x1400, v68
	v_add_u32_e32 v46, 0x1600, v68
	v_add_u32_e32 v52, 0x1800, v68
	v_add_u32_e32 v54, 0x1a00, v68
	v_add_u32_e32 v60, 0x1c00, v68
	v_add_u32_e32 v66, 0x1e00, v68
	v_add_u32_e32 v12, s29, v178
	v_add_u32_e32 v14, s29, v180
	v_add_u32_e32 v20, s29, v181
	v_add_u32_e32 v22, s29, v183
	v_ashrrev_i32_e32 v184, 5, v28
	v_ashrrev_i32_e32 v186, 5, v30
	v_ashrrev_i32_e32 v195, 5, v36
	v_ashrrev_i32_e32 v197, 5, v38
	v_ashrrev_i32_e32 v199, 5, v44
	v_ashrrev_i32_e32 v201, 5, v46
	v_ashrrev_i32_e32 v203, 5, v52
	v_ashrrev_i32_e32 v204, 5, v54
	v_ashrrev_i32_e32 v206, 5, v60
	v_ashrrev_i32_e32 v207, 5, v66
	v_ashrrev_i32_e32 v13, 31, v12
	v_ashrrev_i32_e32 v15, 31, v14
	v_ashrrev_i32_e32 v21, 31, v20
	v_ashrrev_i32_e32 v23, 31, v22
	v_add_u32_e32 v28, s29, v184
	v_add_u32_e32 v30, s29, v186
	v_add_u32_e32 v36, s29, v195
	v_add_u32_e32 v38, s29, v197
	v_add_u32_e32 v44, s29, v199
	v_add_u32_e32 v46, s29, v201
	v_add_u32_e32 v52, s29, v203
	v_add_u32_e32 v54, s29, v204
	v_add_u32_e32 v60, s29, v206
	v_add_u32_e32 v66, s29, v207
	v_lshlrev_b64 v[12:13], 11, v[12:13]
	v_lshlrev_b64 v[14:15], 11, v[14:15]
	v_lshlrev_b64 v[20:21], 11, v[20:21]
	v_lshlrev_b64 v[22:23], 11, v[22:23]
	v_ashrrev_i32_e32 v29, 31, v28
	v_ashrrev_i32_e32 v31, 31, v30
	v_ashrrev_i32_e32 v37, 31, v36
	v_ashrrev_i32_e32 v39, 31, v38
	v_ashrrev_i32_e32 v45, 31, v44
	v_ashrrev_i32_e32 v47, 31, v46
	v_ashrrev_i32_e32 v53, 31, v52
	v_ashrrev_i32_e32 v55, 31, v54
	v_ashrrev_i32_e32 v61, 31, v60
	v_ashrrev_i32_e32 v67, 31, v66
	v_lshl_add_u64 v[12:13], v[64:65], 0, v[12:13]
	v_lshl_add_u64 v[16:17], v[64:65], 0, v[14:15]
	v_lshl_add_u64 v[20:21], v[64:65], 0, v[20:21]
	v_lshl_add_u64 v[24:25], v[64:65], 0, v[22:23]
	v_lshlrev_b64 v[28:29], 11, v[28:29]
	v_lshlrev_b64 v[30:31], 11, v[30:31]
	v_lshlrev_b64 v[36:37], 11, v[36:37]
	v_lshlrev_b64 v[38:39], 11, v[38:39]
	v_lshlrev_b64 v[44:45], 11, v[44:45]
	v_lshlrev_b64 v[46:47], 11, v[46:47]
	v_lshlrev_b64 v[52:53], 11, v[52:53]
	v_lshlrev_b64 v[54:55], 11, v[54:55]
	v_lshlrev_b64 v[60:61], 11, v[60:61]
	v_lshlrev_b64 v[66:67], 11, v[66:67]
	global_load_dwordx4 v[12:15], v[12:13], off
	s_nop 0
	global_load_dwordx4 v[16:19], v[16:17], off
	s_nop 0
	global_load_dwordx4 v[20:23], v[20:21], off
	s_nop 0
	global_load_dwordx4 v[24:27], v[24:25], off
	v_lshl_add_u64 v[28:29], v[64:65], 0, v[28:29]
	v_lshl_add_u64 v[32:33], v[64:65], 0, v[30:31]
	v_lshl_add_u64 v[36:37], v[64:65], 0, v[36:37]
	v_lshl_add_u64 v[40:41], v[64:65], 0, v[38:39]
	v_lshl_add_u64 v[44:45], v[64:65], 0, v[44:45]
	v_lshl_add_u64 v[48:49], v[64:65], 0, v[46:47]
	v_lshl_add_u64 v[52:53], v[64:65], 0, v[52:53]
	v_lshl_add_u64 v[56:57], v[64:65], 0, v[54:55]
	v_lshl_add_u64 v[60:61], v[64:65], 0, v[60:61]
	v_lshl_add_u64 v[64:65], v[64:65], 0, v[66:67]
	global_load_dwordx4 v[28:31], v[28:29], off
	s_nop 0
	global_load_dwordx4 v[32:35], v[32:33], off
	s_nop 0
	global_load_dwordx4 v[36:39], v[36:37], off
	s_nop 0
	global_load_dwordx4 v[40:43], v[40:41], off
	s_nop 0
	global_load_dwordx4 v[44:47], v[44:45], off
	s_nop 0
	global_load_dwordx4 v[48:51], v[48:49], off
	s_nop 0
	global_load_dwordx4 v[52:55], v[52:53], off
	s_nop 0
	global_load_dwordx4 v[56:59], v[56:57], off
	v_bitop3_b32 v72, v176, v69, 15 bitop3:0x6c
	global_load_dwordx4 v[60:63], v[60:61], off
	v_lshlrev_b32_e32 v71, 9, v176
	global_load_dwordx4 v[64:67], v[64:65], off
	v_lshlrev_b32_e32 v72, 4, v72
	v_add3_u32 v179, 16, v71, v72
	s_waitcnt vmcnt(15)
; #define LAS __attribute__((address_space(3)))
; DI void attn_prompt_item(const Params& p, int item, ldsp lds, int tid_) {
;     ...
;     for (int i = 0; i < 8; ++i) { const int idx = tid + 512 * (hb * 8 + i), key = idx >> 5, c = idx & 31; *(LAS u32x4*)(lds + key * 512 + ((c ^ (key & 15)) * 16)) = kp[i]; }
;   }
;   __syncthreads();
;   f32x16 S[8];
; #pragma unroll
;   for (int kt = 0; kt < 8; ++kt)
; #pragma unroll
;     for (int i = 0; i < 16; ++i) S[kt][i] = 0.f;
; #pragma unroll
;   for (int sh = 0; sh < 2; ++sh) {
;     if (sh == 1) {
;       __builtin_amdgcn_sched_barrier(0);
; #pragma unroll
;       for (int s = 0; s < 8; ++s) qreg[s] = *(const bf16x8*)(qx + qrow * D + h * 256 + 16 * (8 + s) + 8 * h2);
;     }
;     {
;       bf16x8 kfa[4], kfb[4];
;     ...
; #pragma unroll
;       for (int j = 0; j < 4; ++j) kfa[j] = *(const LAS bf16x8*)KF_ADDR(0, j);
; #pragma unroll
;       for (int gi = 0; gi < 16; ++gi) {
;         if (gi + 1 < 16) {
; #pragma unroll
;           for (int j = 0; j < 4; ++j) { if (gi & 1) kfa[j] = *(const LAS bf16x8*)KF_ADDR(gi + 1, j); else kfb[j] = *(const LAS bf16x8*)KF_ADDR(gi + 1, j); } }
; #pragma unroll
;         for (int j = 0; j < 4; ++j) S[gi >> 1] = __builtin_amdgcn_mfma_f32_32x32x16_bf16((gi & 1) ? kfb[j] : kfa[j], qreg[(gi & 1) * 4 + j], S[gi >> 1], 0, 0, 0);
;         __builtin_amdgcn_sched_barrier(0);
;       }
	ds_write_b128 v179, v[4:7]
	v_bitop3_b32 v5, v177, v69, 15 bitop3:0x6c
	v_lshlrev_b32_e32 v4, 9, v177
	v_lshlrev_b32_e32 v5, 4, v5
	v_add3_u32 v182, 16, v4, v5
	v_bitop3_b32 v5, v178, v69, 15 bitop3:0x6c
	v_lshlrev_b32_e32 v4, 9, v178
	v_lshlrev_b32_e32 v5, 4, v5
	v_add3_u32 v185, 16, v4, v5
	v_bitop3_b32 v5, v180, v69, 15 bitop3:0x6c
	v_lshlrev_b32_e32 v4, 9, v180
	v_lshlrev_b32_e32 v5, 4, v5
	v_add3_u32 v187, 16, v4, v5
	v_bitop3_b32 v5, v181, v69, 15 bitop3:0x6c
	v_lshlrev_b32_e32 v4, 9, v181
	v_lshlrev_b32_e32 v5, 4, v5
	v_add3_u32 v188, 16, v4, v5
	v_bitop3_b32 v5, v183, v69, 15 bitop3:0x6c
	v_lshlrev_b32_e32 v4, 9, v183
	v_lshlrev_b32_e32 v5, 4, v5
	v_add3_u32 v189, 16, v4, v5
	v_bitop3_b32 v5, v184, v69, 15 bitop3:0x6c
	v_lshlrev_b32_e32 v4, 9, v184
	v_lshlrev_b32_e32 v5, 4, v5
	v_add3_u32 v190, 16, v4, v5
	v_bitop3_b32 v5, v186, v69, 15 bitop3:0x6c
	v_lshlrev_b32_e32 v4, 9, v186
	v_lshlrev_b32_e32 v5, 4, v5
	v_add3_u32 v191, 16, v4, v5
	v_bitop3_b32 v5, v195, v69, 15 bitop3:0x6c
	v_lshlrev_b32_e32 v4, 9, v195
	v_lshlrev_b32_e32 v5, 4, v5
	v_add3_u32 v192, 16, v4, v5
	v_bitop3_b32 v5, v197, v69, 15 bitop3:0x6c
	v_lshlrev_b32_e32 v4, 9, v197
	v_lshlrev_b32_e32 v5, 4, v5
	v_add3_u32 v193, 16, v4, v5
	v_bitop3_b32 v5, v199, v69, 15 bitop3:0x6c
	v_lshlrev_b32_e32 v4, 9, v199
	v_lshlrev_b32_e32 v5, 4, v5
	v_add3_u32 v194, 16, v4, v5
	v_bitop3_b32 v5, v201, v69, 15 bitop3:0x6c
	v_lshlrev_b32_e32 v4, 9, v201
	v_lshlrev_b32_e32 v5, 4, v5
	v_add3_u32 v196, 16, v4, v5
	v_bitop3_b32 v5, v203, v69, 15 bitop3:0x6c
	v_lshlrev_b32_e32 v4, 9, v203
	v_lshlrev_b32_e32 v5, 4, v5
	v_add3_u32 v200, 16, v4, v5
	v_bitop3_b32 v5, v204, v69, 15 bitop3:0x6c
	v_lshlrev_b32_e32 v4, 9, v204
	v_lshlrev_b32_e32 v5, 4, v5
	v_add3_u32 v198, 16, v4, v5
	v_bitop3_b32 v5, v206, v69, 15 bitop3:0x6c
	v_lshlrev_b32_e32 v4, 9, v206
	v_lshlrev_b32_e32 v5, 4, v5
	v_add3_u32 v202, 16, v4, v5
	v_bitop3_b32 v5, v207, v69, 15 bitop3:0x6c
	v_lshrrev_b32_e32 v70, 5, v68
	v_lshlrev_b32_e32 v4, 9, v207
	v_lshlrev_b32_e32 v5, 4, v5
	v_and_b32_e32 v175, 15, v68
	v_add3_u32 v205, 16, v4, v5
	v_lshlrev_b32_e32 v172, 9, v69
	v_bitop3_b32 v4, v70, v175, 1 bitop3:0x6c
	v_add_u32_e32 v173, 16, v172
	v_lshlrev_b32_e32 v209, 4, v4
	s_waitcnt vmcnt(14)
	ds_write_b128 v182, v[8:11]
	s_waitcnt vmcnt(13)
	ds_write_b128 v185, v[12:15]
	s_waitcnt vmcnt(12)
	ds_write_b128 v187, v[16:19]
	s_waitcnt vmcnt(11)
	ds_write_b128 v188, v[20:23]
	s_waitcnt vmcnt(10)
	ds_write_b128 v189, v[24:27]
	v_add_u32_e32 v24, v173, v209
	s_waitcnt vmcnt(9)
	ds_write_b128 v190, v[28:31]
	s_waitcnt vmcnt(8)
	ds_write_b128 v191, v[32:35]
	s_waitcnt vmcnt(7)
	ds_write_b128 v192, v[36:39]
	s_waitcnt vmcnt(6)
	ds_write_b128 v193, v[40:43]
	s_waitcnt vmcnt(5)
	ds_write_b128 v194, v[44:47]
	s_waitcnt vmcnt(4)
	ds_write_b128 v196, v[48:51]
	s_waitcnt vmcnt(3)
	ds_write_b128 v200, v[52:55]
	s_waitcnt vmcnt(2)
	ds_write_b128 v198, v[56:59]
	s_waitcnt vmcnt(1)
	ds_write_b128 v202, v[60:63]
	s_waitcnt vmcnt(0)
	ds_write_b128 v205, v[64:67]
	s_waitcnt lgkmcnt(0)
	s_barrier
	ds_read_b128 v[4:7], v24
	v_bitop3_b32 v8, v208, v175, 2 bitop3:0x36
	v_lshlrev_b32_e32 v210, 4, v8
	v_add_u32_e32 v25, v173, v210
	ds_read_b128 v[8:11], v25
	s_waitcnt lgkmcnt(1)
	v_mfma_f32_32x32x16_bf16 v[112:127], v[4:7], v[0:3], 0
	v_bitop3_b32 v12, v208, v175, 4 bitop3:0x36
	v_lshlrev_b32_e32 v211, 4, v12
	v_bitop3_b32 v4, v208, v175, 6 bitop3:0x36
	v_add_u32_e32 v26, v173, v211
	v_lshlrev_b32_e32 v218, 4, v4
	v_add_u32_e32 v27, v173, v218
	ds_read_b128 v[4:7], v26
	ds_read_b128 v[12:15], v27
	s_waitcnt lgkmcnt(2)
	v_mfma_f32_32x32x16_bf16 v[112:127], v[8:11], v[152:155], v[112:127]
	v_bitop3_b32 v16, v208, v175, 8 bitop3:0x36
	v_bitop3_b32 v20, v208, v175, 12 bitop3:0x36
	v_lshlrev_b32_e32 v226, 4, v16
	v_bitop3_b32 v8, v208, v175, 10 bitop3:0x36
	v_lshlrev_b32_e32 v228, 4, v20
	v_add_u32_e32 v28, v173, v226
	v_lshlrev_b32_e32 v227, 4, v8
	s_waitcnt lgkmcnt(1)
	v_mfma_f32_32x32x16_bf16 v[112:127], v[4:7], v[148:151], v[112:127]
	v_bitop3_b32 v4, v208, v175, 14 bitop3:0x36
	v_add_u32_e32 v30, v173, v228
	v_lshlrev_b32_e32 v229, 4, v4
	v_add_u32_e32 v29, v173, v227
	ds_read_b128 v[8:11], v28
	ds_read_b128 v[16:19], v29
	v_add_u32_e32 v31, v173, v229
	ds_read_b128 v[4:7], v30
	ds_read_b128 v[20:23], v31
	v_lshlrev_b32_e32 v160, 3, v208
	s_waitcnt lgkmcnt(4)
	v_mfma_f32_32x32x16_bf16 v[112:127], v[12:15], v[144:147], v[112:127]
	s_waitcnt lgkmcnt(3)
	v_mfma_f32_32x32x16_bf16 v[112:127], v[8:11], v[140:143], v[112:127]
	s_waitcnt lgkmcnt(2)
	v_mfma_f32_32x32x16_bf16 v[112:127], v[16:19], v[136:139], v[112:127]
	s_waitcnt lgkmcnt(1)
	v_mfma_f32_32x32x16_bf16 v[112:127], v[4:7], v[132:135], v[112:127]
	ds_read_b128 v[4:7], v24 offset:16384
	ds_read_b128 v[8:11], v25 offset:16384
	ds_read_b128 v[12:15], v26 offset:16384
	ds_read_b128 v[16:19], v27 offset:16384
	s_waitcnt lgkmcnt(4)
	v_mfma_f32_32x32x16_bf16 v[112:127], v[20:23], v[128:131], v[112:127]
	s_waitcnt lgkmcnt(3)
	v_mfma_f32_32x32x16_bf16 v[96:111], v[4:7], v[0:3], 0
	s_waitcnt lgkmcnt(2)
	v_mfma_f32_32x32x16_bf16 v[96:111], v[8:11], v[152:155], v[96:111]
	s_waitcnt lgkmcnt(1)
	v_mfma_f32_32x32x16_bf16 v[96:111], v[12:15], v[148:151], v[96:111]
	ds_read_b128 v[4:7], v28 offset:16384
	ds_read_b128 v[8:11], v29 offset:16384
	ds_read_b128 v[12:15], v30 offset:16384
	ds_read_b128 v[20:23], v31 offset:16384
	s_waitcnt lgkmcnt(4)
	v_mfma_f32_32x32x16_bf16 v[96:111], v[16:19], v[144:147], v[96:111]
	s_waitcnt lgkmcnt(3)
	v_mfma_f32_32x32x16_bf16 v[96:111], v[4:7], v[140:143], v[96:111]
	s_waitcnt lgkmcnt(2)
	v_mfma_f32_32x32x16_bf16 v[96:111], v[8:11], v[136:139], v[96:111]
	s_waitcnt lgkmcnt(1)
; #define LAS __attribute__((address_space(3)))
; DI void attn_prompt_item(const Params& p, int item, ldsp lds, int tid_) {
;     ...
; #pragma unroll
;       for (int j = 0; j < 4; ++j) kfa[j] = *(const LAS bf16x8*)KF_ADDR(0, j);
; #pragma unroll
;       for (int gi = 0; gi < 16; ++gi) {
;         if (gi + 1 < 16) {
; #pragma unroll
;           for (int j = 0; j < 4; ++j) { if (gi & 1) kfa[j] = *(const LAS bf16x8*)KF_ADDR(gi + 1, j); else kfb[j] = *(const LAS bf16x8*)KF_ADDR(gi + 1, j); } }
; #pragma unroll
;         for (int j = 0; j < 4; ++j) S[gi >> 1] = __builtin_amdgcn_mfma_f32_32x32x16_bf16((gi & 1) ? kfb[j] : kfa[j], qreg[(gi & 1) * 4 + j], S[gi >> 1], 0, 0, 0);
;         __builtin_amdgcn_sched_barrier(0);
;       }
	v_mfma_f32_32x32x16_bf16 v[96:111], v[12:15], v[132:135], v[96:111]
	ds_read_b128 v[4:7], v24 offset:32768
	ds_read_b128 v[8:11], v25 offset:32768
	ds_read_b128 v[12:15], v26 offset:32768
	ds_read_b128 v[16:19], v27 offset:32768
	s_waitcnt lgkmcnt(4)
	v_mfma_f32_32x32x16_bf16 v[96:111], v[20:23], v[128:131], v[96:111]
	s_waitcnt lgkmcnt(3)
	v_mfma_f32_32x32x16_bf16 v[80:95], v[4:7], v[0:3], 0
	s_waitcnt lgkmcnt(2)
	v_mfma_f32_32x32x16_bf16 v[80:95], v[8:11], v[152:155], v[80:95]
	s_waitcnt lgkmcnt(1)
	v_mfma_f32_32x32x16_bf16 v[80:95], v[12:15], v[148:151], v[80:95]
	ds_read_b128 v[4:7], v28 offset:32768
	ds_read_b128 v[8:11], v29 offset:32768
	ds_read_b128 v[12:15], v30 offset:32768
	ds_read_b128 v[20:23], v31 offset:32768
	s_waitcnt lgkmcnt(4)
	v_mfma_f32_32x32x16_bf16 v[80:95], v[16:19], v[144:147], v[80:95]
	s_waitcnt lgkmcnt(3)
	v_mfma_f32_32x32x16_bf16 v[80:95], v[4:7], v[140:143], v[80:95]
	s_waitcnt lgkmcnt(2)
	v_mfma_f32_32x32x16_bf16 v[80:95], v[8:11], v[136:139], v[80:95]
	s_waitcnt lgkmcnt(1)
	v_mfma_f32_32x32x16_bf16 v[80:95], v[12:15], v[132:135], v[80:95]
	ds_read_b128 v[4:7], v24 offset:49152
	ds_read_b128 v[8:11], v25 offset:49152
	ds_read_b128 v[12:15], v26 offset:49152
	ds_read_b128 v[16:19], v27 offset:49152
	s_waitcnt lgkmcnt(4)
	v_mfma_f32_32x32x16_bf16 v[80:95], v[20:23], v[128:131], v[80:95]
	s_waitcnt lgkmcnt(3)
	v_mfma_f32_32x32x16_bf16 v[64:79], v[4:7], v[0:3], 0
	s_waitcnt lgkmcnt(2)
	v_mfma_f32_32x32x16_bf16 v[64:79], v[8:11], v[152:155], v[64:79]
	s_waitcnt lgkmcnt(1)
	v_mfma_f32_32x32x16_bf16 v[64:79], v[12:15], v[148:151], v[64:79]
	ds_read_b128 v[4:7], v28 offset:49152
	ds_read_b128 v[8:11], v29 offset:49152
	ds_read_b128 v[12:15], v30 offset:49152
	ds_read_b128 v[20:23], v31 offset:49152
	s_waitcnt lgkmcnt(4)
	v_mfma_f32_32x32x16_bf16 v[64:79], v[16:19], v[144:147], v[64:79]
	s_waitcnt lgkmcnt(3)
	v_mfma_f32_32x32x16_bf16 v[64:79], v[4:7], v[140:143], v[64:79]
	v_add_u32_e32 v230, 0x10000, v173
	v_add_u32_e32 v4, v230, v209
	v_add_u32_e32 v16, v230, v218
	s_waitcnt lgkmcnt(2)
	v_mfma_f32_32x32x16_bf16 v[64:79], v[8:11], v[136:139], v[64:79]
	v_add_u32_e32 v8, v230, v210
	ds_read_b128 v[4:7], v4
	ds_read_b128 v[8:11], v8
	s_waitcnt lgkmcnt(3)
	v_mfma_f32_32x32x16_bf16 v[64:79], v[12:15], v[132:135], v[64:79]
	v_add_u32_e32 v12, v230, v211
	ds_read_b128 v[12:15], v12
	ds_read_b128 v[16:19], v16
	s_waitcnt lgkmcnt(4)
	v_mfma_f32_32x32x16_bf16 v[64:79], v[20:23], v[128:131], v[64:79]
	s_waitcnt lgkmcnt(3)
	v_mfma_f32_32x32x16_bf16 v[48:63], v[4:7], v[0:3], 0
	v_add_u32_e32 v4, v230, v226
	v_add_u32_e32 v20, v230, v229
	s_waitcnt lgkmcnt(2)
	v_mfma_f32_32x32x16_bf16 v[48:63], v[8:11], v[152:155], v[48:63]
	v_add_u32_e32 v8, v230, v227
	ds_read_b128 v[4:7], v4
	ds_read_b128 v[8:11], v8
	s_waitcnt lgkmcnt(3)
	v_mfma_f32_32x32x16_bf16 v[48:63], v[12:15], v[148:151], v[48:63]
	v_add_u32_e32 v12, v230, v228
	ds_read_b128 v[12:15], v12
	ds_read_b128 v[20:23], v20
	s_waitcnt lgkmcnt(4)
	v_mfma_f32_32x32x16_bf16 v[48:63], v[16:19], v[144:147], v[48:63]
	s_waitcnt lgkmcnt(3)
	v_mfma_f32_32x32x16_bf16 v[48:63], v[4:7], v[140:143], v[48:63]
	v_add_u32_e32 v231, 0x14000, v173
	v_add_u32_e32 v4, v231, v209
	v_add_u32_e32 v16, v231, v218
	s_waitcnt lgkmcnt(2)
	v_mfma_f32_32x32x16_bf16 v[48:63], v[8:11], v[136:139], v[48:63]
	v_add_u32_e32 v8, v231, v210
	ds_read_b128 v[4:7], v4
	ds_read_b128 v[8:11], v8
	s_waitcnt lgkmcnt(3)
	v_mfma_f32_32x32x16_bf16 v[48:63], v[12:15], v[132:135], v[48:63]
	v_add_u32_e32 v12, v231, v211
	ds_read_b128 v[12:15], v12
	ds_read_b128 v[16:19], v16
	s_waitcnt lgkmcnt(4)
	v_mfma_f32_32x32x16_bf16 v[48:63], v[20:23], v[128:131], v[48:63]
	s_waitcnt lgkmcnt(3)
	v_mfma_f32_32x32x16_bf16 v[32:47], v[4:7], v[0:3], 0
	v_add_u32_e32 v4, v231, v226
	v_add_u32_e32 v20, v231, v229
	s_waitcnt lgkmcnt(2)
	v_mfma_f32_32x32x16_bf16 v[32:47], v[8:11], v[152:155], v[32:47]
	v_add_u32_e32 v8, v231, v227
	ds_read_b128 v[4:7], v4
	ds_read_b128 v[8:11], v8
	s_waitcnt lgkmcnt(3)
	v_mfma_f32_32x32x16_bf16 v[32:47], v[12:15], v[148:151], v[32:47]
	v_add_u32_e32 v12, v231, v228
	ds_read_b128 v[12:15], v12
	ds_read_b128 v[20:23], v20
	s_waitcnt lgkmcnt(4)
	v_mfma_f32_32x32x16_bf16 v[32:47], v[16:19], v[144:147], v[32:47]
	s_waitcnt lgkmcnt(3)
	v_mfma_f32_32x32x16_bf16 v[32:47], v[4:7], v[140:143], v[32:47]
	v_add_u32_e32 v232, 0x18000, v173
	v_add_u32_e32 v4, v232, v209
	v_add_u32_e32 v16, v232, v218
	s_waitcnt lgkmcnt(2)
	v_mfma_f32_32x32x16_bf16 v[32:47], v[8:11], v[136:139], v[32:47]
	v_add_u32_e32 v8, v232, v210
	ds_read_b128 v[4:7], v4
	ds_read_b128 v[8:11], v8
	s_waitcnt lgkmcnt(3)
	v_mfma_f32_32x32x16_bf16 v[32:47], v[12:15], v[132:135], v[32:47]
	v_add_u32_e32 v12, v232, v211
	ds_read_b128 v[12:15], v12
	ds_read_b128 v[156:159], v16
	s_waitcnt lgkmcnt(4)
	v_mfma_f32_32x32x16_bf16 v[32:47], v[20:23], v[128:131], v[32:47]
	s_waitcnt lgkmcnt(3)
	v_mfma_f32_32x32x16_bf16 v[16:31], v[4:7], v[0:3], 0
	v_add_u32_e32 v4, v232, v226
	v_add_u32_e32 v214, v232, v229
	s_waitcnt lgkmcnt(2)
	v_mfma_f32_32x32x16_bf16 v[16:31], v[8:11], v[152:155], v[16:31]
	v_add_u32_e32 v8, v232, v227
	ds_read_b128 v[4:7], v4
	ds_read_b128 v[8:11], v8
	s_waitcnt lgkmcnt(3)
	v_mfma_f32_32x32x16_bf16 v[16:31], v[12:15], v[148:151], v[16:31]
	v_add_u32_e32 v12, v232, v228
	ds_read_b128 v[12:15], v12
	ds_read_b128 v[214:217], v214
	s_waitcnt lgkmcnt(4)
	v_mfma_f32_32x32x16_bf16 v[16:31], v[156:159], v[144:147], v[16:31]
	s_waitcnt lgkmcnt(3)
	v_mfma_f32_32x32x16_bf16 v[16:31], v[4:7], v[140:143], v[16:31]
	v_add_u32_e32 v233, 0x1c000, v173
	v_add_u32_e32 v4, v233, v209
	s_waitcnt lgkmcnt(2)
; #define LAS __attribute__((address_space(3)))
; DI void attn_prompt_item(const Params& p, int item, ldsp lds, int tid_) {
;     ...
;     if (sh == 1) {
;       __builtin_amdgcn_sched_barrier(0);
; #pragma unroll
;       for (int s = 0; s < 8; ++s) qreg[s] = *(const bf16x8*)(qx + qrow * D + h * 256 + 16 * (8 + s) + 8 * h2);
;     }
;     {
;       bf16x8 kfa[4], kfb[4];
;     ...
; #pragma unroll
;       for (int j = 0; j < 4; ++j) kfa[j] = *(const LAS bf16x8*)KF_ADDR(0, j);
; #pragma unroll
;       for (int gi = 0; gi < 16; ++gi) {
;         if (gi + 1 < 16) {
; #pragma unroll
;           for (int j = 0; j < 4; ++j) { if (gi & 1) kfa[j] = *(const LAS bf16x8*)KF_ADDR(gi + 1, j); else kfb[j] = *(const LAS bf16x8*)KF_ADDR(gi + 1, j); } }
; #pragma unroll
;         for (int j = 0; j < 4; ++j) S[gi >> 1] = __builtin_amdgcn_mfma_f32_32x32x16_bf16((gi & 1) ? kfb[j] : kfa[j], qreg[(gi & 1) * 4 + j], S[gi >> 1], 0, 0, 0);
;         __builtin_amdgcn_sched_barrier(0);
;       }
	v_mfma_f32_32x32x16_bf16 v[16:31], v[8:11], v[136:139], v[16:31]
	v_add_u32_e32 v8, v233, v210
	ds_read_b128 v[4:7], v4
	ds_read_b128 v[156:159], v8
	v_add_u32_e32 v8, v233, v211
	v_add_u32_e32 v9, v233, v218
	ds_read_b128 v[218:221], v8
	ds_read_b128 v[222:225], v9
	s_waitcnt lgkmcnt(5)
	v_mfma_f32_32x32x16_bf16 v[16:31], v[12:15], v[132:135], v[16:31]
	s_waitcnt lgkmcnt(4)
	v_mfma_f32_32x32x16_bf16 v[16:31], v[214:217], v[128:131], v[16:31]
	s_waitcnt lgkmcnt(3)
	v_mfma_f32_32x32x16_bf16 v[0:15], v[4:7], v[0:3], 0
	v_add_u32_e32 v209, v233, v229
	s_waitcnt lgkmcnt(2)
	v_mfma_f32_32x32x16_bf16 v[0:15], v[156:159], v[152:155], v[0:15]
	v_add_u32_e32 v152, v233, v226
	v_add_u32_e32 v153, v233, v227
	v_add_u32_e32 v156, v233, v228
	s_waitcnt lgkmcnt(1)
	v_mfma_f32_32x32x16_bf16 v[0:15], v[218:221], v[148:151], v[0:15]
	ds_read_b128 v[148:151], v152
	ds_read_b128 v[152:155], v153
	ds_read_b128 v[156:159], v156
	ds_read_b128 v[214:217], v209
	s_waitcnt lgkmcnt(4)
	v_mfma_f32_32x32x16_bf16 v[0:15], v[222:225], v[144:147], v[0:15]
	s_waitcnt lgkmcnt(3)
	v_mfma_f32_32x32x16_bf16 v[0:15], v[148:151], v[140:143], v[0:15]
	s_waitcnt lgkmcnt(2)
	v_mfma_f32_32x32x16_bf16 v[0:15], v[152:155], v[136:139], v[0:15]
	s_waitcnt lgkmcnt(1)
	v_mfma_f32_32x32x16_bf16 v[0:15], v[156:159], v[132:135], v[0:15]
	s_waitcnt lgkmcnt(0)
	v_mfma_f32_32x32x16_bf16 v[0:15], v[214:217], v[128:131], v[0:15]
	global_load_dwordx4 v[156:159], v[166:167], off offset:256
	global_load_dwordx4 v[152:155], v[166:167], off offset:288
	global_load_dwordx4 v[148:151], v[166:167], off offset:320
	global_load_dwordx4 v[144:147], v[166:167], off offset:352
	global_load_dwordx4 v[140:143], v[166:167], off offset:384
	global_load_dwordx4 v[136:139], v[166:167], off offset:416
	global_load_dwordx4 v[132:135], v[166:167], off offset:448
	global_load_dwordx4 v[128:131], v[166:167], off offset:480
	v_bitop3_b32 v166, v208, v175, 16 bitop3:0x36
	v_lshlrev_b32_e32 v166, 4, v166
	v_add_u32_e32 v167, v173, v166
	ds_read_b128 v[214:217], v167
	v_bitop3_b32 v209, v208, v175, 18 bitop3:0x36
	v_lshlrev_b32_e32 v234, 4, v209
	v_add_u32_e32 v235, v173, v234
	ds_read_b128 v[218:221], v235
	v_bitop3_b32 v209, v208, v175, 20 bitop3:0x36
	v_lshlrev_b32_e32 v236, 4, v209
	v_bitop3_b32 v209, v208, v175, 22 bitop3:0x36
	v_add_u32_e32 v237, v173, v236
	v_lshlrev_b32_e32 v238, 4, v209
	v_add_u32_e32 v239, v173, v238
	v_bitop3_b32 v209, v208, v175, 24 bitop3:0x36
	v_lshlrev_b32_e32 v240, 4, v209
	v_bitop3_b32 v209, v208, v175, 26 bitop3:0x36
	v_lshlrev_b32_e32 v242, 4, v209
	v_bitop3_b32 v209, v208, v175, 28 bitop3:0x36
	v_lshlrev_b32_e32 v244, 4, v209
	v_bitop3_b32 v208, v208, v175, 30 bitop3:0x36
	v_add_u32_e32 v241, v173, v240
	v_add_u32_e32 v245, v173, v244
	v_lshlrev_b32_e32 v246, 4, v208
	v_add_u32_e32 v243, v173, v242
	v_add_u32_e32 v247, v173, v246
	s_waitcnt vmcnt(7) lgkmcnt(1)
	v_mfma_f32_32x32x16_bf16 v[112:127], v[214:217], v[156:159], v[112:127]
	ds_read_b128 v[214:217], v237
	ds_read_b128 v[222:225], v239
	s_waitcnt vmcnt(6) lgkmcnt(2)
	v_mfma_f32_32x32x16_bf16 v[112:127], v[218:221], v[152:155], v[112:127]
	ds_read_b128 v[218:221], v241
	ds_read_b128 v[226:229], v243
	s_waitcnt vmcnt(5) lgkmcnt(3)
	v_mfma_f32_32x32x16_bf16 v[112:127], v[214:217], v[148:151], v[112:127]
	ds_read_b128 v[208:211], v245
	ds_read_b128 v[214:217], v247
	s_waitcnt vmcnt(4) lgkmcnt(4)
	v_mfma_f32_32x32x16_bf16 v[112:127], v[222:225], v[144:147], v[112:127]
	s_waitcnt vmcnt(3) lgkmcnt(3)
	v_mfma_f32_32x32x16_bf16 v[112:127], v[218:221], v[140:143], v[112:127]
	s_waitcnt vmcnt(2) lgkmcnt(2)
	v_mfma_f32_32x32x16_bf16 v[112:127], v[226:229], v[136:139], v[112:127]
	s_waitcnt vmcnt(1) lgkmcnt(1)
	v_mfma_f32_32x32x16_bf16 v[112:127], v[208:211], v[132:135], v[112:127]
	ds_read_b128 v[208:211], v167 offset:16384
	ds_read_b128 v[218:221], v235 offset:16384
	ds_read_b128 v[222:225], v237 offset:16384
	ds_read_b128 v[226:229], v239 offset:16384
	s_waitcnt vmcnt(0) lgkmcnt(4)
	v_mfma_f32_32x32x16_bf16 v[112:127], v[214:217], v[128:131], v[112:127]
	s_waitcnt lgkmcnt(3)
	v_mfma_f32_32x32x16_bf16 v[96:111], v[208:211], v[156:159], v[96:111]
	s_waitcnt lgkmcnt(2)
	v_mfma_f32_32x32x16_bf16 v[96:111], v[218:221], v[152:155], v[96:111]
	s_waitcnt lgkmcnt(1)
	v_mfma_f32_32x32x16_bf16 v[96:111], v[222:225], v[148:151], v[96:111]
	ds_read_b128 v[208:211], v241 offset:16384
	ds_read_b128 v[214:217], v243 offset:16384
	ds_read_b128 v[218:221], v245 offset:16384
	ds_read_b128 v[222:225], v247 offset:16384
	s_waitcnt lgkmcnt(4)
	v_mfma_f32_32x32x16_bf16 v[96:111], v[226:229], v[144:147], v[96:111]
	s_waitcnt lgkmcnt(3)
	v_mfma_f32_32x32x16_bf16 v[96:111], v[208:211], v[140:143], v[96:111]
	s_waitcnt lgkmcnt(2)
	v_mfma_f32_32x32x16_bf16 v[96:111], v[214:217], v[136:139], v[96:111]
	s_waitcnt lgkmcnt(1)
	v_mfma_f32_32x32x16_bf16 v[96:111], v[218:221], v[132:135], v[96:111]
	ds_read_b128 v[208:211], v167 offset:32768
	ds_read_b128 v[214:217], v235 offset:32768
	ds_read_b128 v[218:221], v237 offset:32768
	ds_read_b128 v[226:229], v239 offset:32768
	s_waitcnt lgkmcnt(4)
	v_mfma_f32_32x32x16_bf16 v[96:111], v[222:225], v[128:131], v[96:111]
	s_waitcnt lgkmcnt(3)
	v_mfma_f32_32x32x16_bf16 v[80:95], v[208:211], v[156:159], v[80:95]
	s_waitcnt lgkmcnt(2)
	v_mfma_f32_32x32x16_bf16 v[80:95], v[214:217], v[152:155], v[80:95]
	s_waitcnt lgkmcnt(1)
	v_mfma_f32_32x32x16_bf16 v[80:95], v[218:221], v[148:151], v[80:95]
	ds_read_b128 v[208:211], v241 offset:32768
	ds_read_b128 v[214:217], v243 offset:32768
	ds_read_b128 v[218:221], v245 offset:32768
	ds_read_b128 v[222:225], v247 offset:32768
	s_waitcnt lgkmcnt(4)
; #define LAS __attribute__((address_space(3)))
; DI void attn_prompt_item(const Params& p, int item, ldsp lds, int tid_) {
;     ...
; #pragma unroll
;       for (int j = 0; j < 4; ++j) kfa[j] = *(const LAS bf16x8*)KF_ADDR(0, j);
; #pragma unroll
;       for (int gi = 0; gi < 16; ++gi) {
;         if (gi + 1 < 16) {
; #pragma unroll
;           for (int j = 0; j < 4; ++j) { if (gi & 1) kfa[j] = *(const LAS bf16x8*)KF_ADDR(gi + 1, j); else kfb[j] = *(const LAS bf16x8*)KF_ADDR(gi + 1, j); } }
; #pragma unroll
;         for (int j = 0; j < 4; ++j) S[gi >> 1] = __builtin_amdgcn_mfma_f32_32x32x16_bf16((gi & 1) ? kfb[j] : kfa[j], qreg[(gi & 1) * 4 + j], S[gi >> 1], 0, 0, 0);
;         __builtin_amdgcn_sched_barrier(0);
;       }
	v_mfma_f32_32x32x16_bf16 v[80:95], v[226:229], v[144:147], v[80:95]
	s_waitcnt lgkmcnt(3)
	v_mfma_f32_32x32x16_bf16 v[80:95], v[208:211], v[140:143], v[80:95]
	s_waitcnt lgkmcnt(2)
	v_mfma_f32_32x32x16_bf16 v[80:95], v[214:217], v[136:139], v[80:95]
	s_waitcnt lgkmcnt(1)
	v_mfma_f32_32x32x16_bf16 v[80:95], v[218:221], v[132:135], v[80:95]
	ds_read_b128 v[208:211], v167 offset:49152
	ds_read_b128 v[214:217], v235 offset:49152
	ds_read_b128 v[218:221], v237 offset:49152
	ds_read_b128 v[226:229], v239 offset:49152
	s_waitcnt lgkmcnt(4)
	v_mfma_f32_32x32x16_bf16 v[80:95], v[222:225], v[128:131], v[80:95]
	s_waitcnt lgkmcnt(3)
	v_mfma_f32_32x32x16_bf16 v[64:79], v[208:211], v[156:159], v[64:79]
	s_waitcnt lgkmcnt(2)
	v_mfma_f32_32x32x16_bf16 v[64:79], v[214:217], v[152:155], v[64:79]
	s_waitcnt lgkmcnt(1)
	v_mfma_f32_32x32x16_bf16 v[64:79], v[218:221], v[148:151], v[64:79]
	ds_read_b128 v[208:211], v241 offset:49152
	ds_read_b128 v[214:217], v243 offset:49152
	ds_read_b128 v[218:221], v245 offset:49152
	ds_read_b128 v[222:225], v247 offset:49152
	s_waitcnt lgkmcnt(4)
	v_mfma_f32_32x32x16_bf16 v[64:79], v[226:229], v[144:147], v[64:79]
	s_waitcnt lgkmcnt(3)
	v_mfma_f32_32x32x16_bf16 v[64:79], v[208:211], v[140:143], v[64:79]
	v_add_u32_e32 v167, v230, v166
	v_add_u32_e32 v226, v230, v238
	s_waitcnt lgkmcnt(2)
	v_mfma_f32_32x32x16_bf16 v[64:79], v[214:217], v[136:139], v[64:79]
	v_add_u32_e32 v214, v230, v234
	ds_read_b128 v[208:211], v167
	ds_read_b128 v[214:217], v214
	v_add_u32_e32 v167, v230, v236
	s_waitcnt lgkmcnt(3)
	v_mfma_f32_32x32x16_bf16 v[64:79], v[218:221], v[132:135], v[64:79]
	ds_read_b128 v[218:221], v167
	ds_read_b128 v[226:229], v226
	s_waitcnt lgkmcnt(4)
	v_mfma_f32_32x32x16_bf16 v[64:79], v[222:225], v[128:131], v[64:79]
	s_waitcnt lgkmcnt(3)
	v_mfma_f32_32x32x16_bf16 v[48:63], v[208:211], v[156:159], v[48:63]
	v_add_u32_e32 v167, v230, v240
	v_add_u32_e32 v222, v230, v246
	s_waitcnt lgkmcnt(2)
	v_mfma_f32_32x32x16_bf16 v[48:63], v[214:217], v[152:155], v[48:63]
	v_add_u32_e32 v214, v230, v242
	ds_read_b128 v[208:211], v167
	ds_read_b128 v[214:217], v214
	v_add_u32_e32 v167, v230, v244
	s_waitcnt lgkmcnt(3)
	v_mfma_f32_32x32x16_bf16 v[48:63], v[218:221], v[148:151], v[48:63]
	ds_read_b128 v[218:221], v167
	ds_read_b128 v[222:225], v222
	s_waitcnt lgkmcnt(4)
	v_mfma_f32_32x32x16_bf16 v[48:63], v[226:229], v[144:147], v[48:63]
	s_waitcnt lgkmcnt(3)
	v_mfma_f32_32x32x16_bf16 v[48:63], v[208:211], v[140:143], v[48:63]
	v_add_u32_e32 v167, v231, v166
	v_add_u32_e32 v226, v231, v238
	s_waitcnt lgkmcnt(2)
	v_mfma_f32_32x32x16_bf16 v[48:63], v[214:217], v[136:139], v[48:63]
	v_add_u32_e32 v214, v231, v234
	ds_read_b128 v[208:211], v167
	ds_read_b128 v[214:217], v214
	v_add_u32_e32 v167, v231, v236
	s_waitcnt lgkmcnt(3)
	v_mfma_f32_32x32x16_bf16 v[48:63], v[218:221], v[132:135], v[48:63]
	ds_read_b128 v[218:221], v167
	ds_read_b128 v[226:229], v226
	s_waitcnt lgkmcnt(4)
	v_mfma_f32_32x32x16_bf16 v[48:63], v[222:225], v[128:131], v[48:63]
	s_waitcnt lgkmcnt(3)
	v_mfma_f32_32x32x16_bf16 v[32:47], v[208:211], v[156:159], v[32:47]
	v_add_u32_e32 v167, v231, v240
	v_add_u32_e32 v222, v231, v246
	s_waitcnt lgkmcnt(2)
	v_mfma_f32_32x32x16_bf16 v[32:47], v[214:217], v[152:155], v[32:47]
	v_add_u32_e32 v214, v231, v242
	ds_read_b128 v[208:211], v167
	ds_read_b128 v[214:217], v214
	v_add_u32_e32 v167, v231, v244
	s_waitcnt lgkmcnt(3)
	v_mfma_f32_32x32x16_bf16 v[32:47], v[218:221], v[148:151], v[32:47]
	ds_read_b128 v[218:221], v167
	ds_read_b128 v[222:225], v222
	s_waitcnt lgkmcnt(4)
	v_mfma_f32_32x32x16_bf16 v[32:47], v[226:229], v[144:147], v[32:47]
	s_waitcnt lgkmcnt(3)
	v_mfma_f32_32x32x16_bf16 v[32:47], v[208:211], v[140:143], v[32:47]
	v_add_u32_e32 v167, v232, v166
	v_add_u32_e32 v226, v232, v238
	s_waitcnt lgkmcnt(2)
	v_mfma_f32_32x32x16_bf16 v[32:47], v[214:217], v[136:139], v[32:47]
	v_add_u32_e32 v214, v232, v234
	ds_read_b128 v[208:211], v167
	ds_read_b128 v[214:217], v214
	v_add_u32_e32 v167, v232, v236
	s_waitcnt lgkmcnt(3)
	v_mfma_f32_32x32x16_bf16 v[32:47], v[218:221], v[132:135], v[32:47]
	ds_read_b128 v[218:221], v167
	ds_read_b128 v[226:229], v226
	s_waitcnt lgkmcnt(4)
	v_mfma_f32_32x32x16_bf16 v[32:47], v[222:225], v[128:131], v[32:47]
	s_waitcnt lgkmcnt(3)
	v_mfma_f32_32x32x16_bf16 v[16:31], v[208:211], v[156:159], v[16:31]
	v_add_u32_e32 v167, v232, v240
	v_add_u32_e32 v222, v232, v246
	s_waitcnt lgkmcnt(2)
	v_mfma_f32_32x32x16_bf16 v[16:31], v[214:217], v[152:155], v[16:31]
	v_add_u32_e32 v214, v232, v242
	ds_read_b128 v[208:211], v167
	ds_read_b128 v[214:217], v214
	v_add_u32_e32 v167, v232, v244
	s_waitcnt lgkmcnt(3)
	v_mfma_f32_32x32x16_bf16 v[16:31], v[218:221], v[148:151], v[16:31]
	ds_read_b128 v[218:221], v167
	ds_read_b128 v[222:225], v222
	s_waitcnt lgkmcnt(4)
	v_mfma_f32_32x32x16_bf16 v[16:31], v[226:229], v[144:147], v[16:31]
	s_waitcnt lgkmcnt(3)
	v_mfma_f32_32x32x16_bf16 v[16:31], v[208:211], v[140:143], v[16:31]
	v_add_u32_e32 v166, v233, v166
	v_add_u32_e32 v167, v233, v234
	s_waitcnt lgkmcnt(2)
	v_mfma_f32_32x32x16_bf16 v[16:31], v[214:217], v[136:139], v[16:31]
	ds_read_b128 v[208:211], v166
	ds_read_b128 v[214:217], v167
	v_add_u32_e32 v166, v233, v236
	v_add_u32_e32 v167, v233, v238
	s_waitcnt lgkmcnt(3)
	v_mfma_f32_32x32x16_bf16 v[16:31], v[218:221], v[132:135], v[16:31]
	ds_read_b128 v[218:221], v166
	ds_read_b128 v[226:229], v167
	s_waitcnt lgkmcnt(4)
	v_mfma_f32_32x32x16_bf16 v[16:31], v[222:225], v[128:131], v[16:31]
	s_waitcnt lgkmcnt(3)
	v_mfma_f32_32x32x16_bf16 v[0:15], v[208:211], v[156:159], v[0:15]
	v_add_u32_e32 v156, v233, v244
	v_add_u32_e32 v166, v233, v246
	s_waitcnt lgkmcnt(2)
; #define LAS __attribute__((address_space(3)))
; DI void attn_prompt_item(const Params& p, int item, ldsp lds, int tid_) {
;     ...
;   float mx = -1e30f;
; #pragma unroll
;   for (int kt = 0; kt < 8; ++kt)
; #pragma unroll
;     for (int i = 0; i < 16; ++i) mx = fmaxf(mx, S[kt][i]);
;   mx = fmaxf(mx, __shfl_xor(mx, 32));
;     ...
;   __syncthreads();
; #pragma unroll
;   for (int hb = 0; hb < 2; ++hb) {
;     u32x4 vp[8];
; #pragma unroll
;     for (int i = 0; i < 8; ++i) { const int idx = tid + 512 * (hb * 8 + i), d = idx >> 5, c = idx & 31; vp[i] = ld16(mvt + ((size_t)((b * 4 + h) * 256 + d)) * 256 + c * 8); }
; #pragma unroll
;     for (int i = 0; i < 8; ++i) { const int idx = tid + 512 * (hb * 8 + i), d = idx >> 5, c = idx & 31; *(LAS u32x4*)(lds + d * 512 + ((c ^ (d & 15)) * 16)) = vp[i]; }
;   }
	v_mfma_f32_32x32x16_bf16 v[0:15], v[214:217], v[152:155], v[0:15]
	v_add_u32_e32 v152, v233, v240
	v_add_u32_e32 v153, v233, v242
	s_waitcnt lgkmcnt(1)
	v_mfma_f32_32x32x16_bf16 v[0:15], v[218:221], v[148:151], v[0:15]
	ds_read_b128 v[148:151], v152
	ds_read_b128 v[152:155], v153
	ds_read_b128 v[156:159], v156
	ds_read_b128 v[208:211], v166
	s_waitcnt lgkmcnt(4)
	v_mfma_f32_32x32x16_bf16 v[0:15], v[226:229], v[144:147], v[0:15]
	s_waitcnt lgkmcnt(3)
	v_mfma_f32_32x32x16_bf16 v[0:15], v[148:151], v[140:143], v[0:15]
	s_waitcnt lgkmcnt(2)
	v_mfma_f32_32x32x16_bf16 v[0:15], v[152:155], v[136:139], v[0:15]
	s_waitcnt lgkmcnt(1)
	v_mfma_f32_32x32x16_bf16 v[0:15], v[156:159], v[132:135], v[0:15]
	s_waitcnt lgkmcnt(0)
	v_mfma_f32_32x32x16_bf16 v[0:15], v[208:211], v[128:131], v[0:15]
	v_max3_f32 v128, v112, s35, v113
	v_max3_f32 v128, v128, v114, v115
	v_max3_f32 v128, v128, v116, v117
	v_max3_f32 v128, v128, v118, v119
	v_max3_f32 v128, v128, v120, v121
	v_max3_f32 v128, v128, v122, v123
	v_max3_f32 v128, v128, v124, v125
	v_max3_f32 v128, v128, v126, v127
	v_max3_f32 v128, v128, v96, v97
	v_max3_f32 v128, v128, v98, v99
	v_max3_f32 v128, v128, v100, v101
	v_max3_f32 v128, v128, v102, v103
	v_max3_f32 v128, v128, v104, v105
	v_max3_f32 v128, v128, v106, v107
	v_max3_f32 v128, v128, v108, v109
	v_max3_f32 v128, v128, v110, v111
	v_max3_f32 v128, v128, v80, v81
	v_max3_f32 v128, v128, v82, v83
	v_max3_f32 v128, v128, v84, v85
	v_max3_f32 v128, v128, v86, v87
	v_max3_f32 v128, v128, v88, v89
	v_max3_f32 v128, v128, v90, v91
	v_max3_f32 v128, v128, v92, v93
	v_max3_f32 v128, v128, v94, v95
	v_max3_f32 v128, v128, v64, v65
	v_max3_f32 v128, v128, v66, v67
	v_max3_f32 v128, v128, v68, v69
	v_max3_f32 v128, v128, v70, v71
	v_max3_f32 v128, v128, v72, v73
	v_max3_f32 v128, v128, v74, v75
	v_max3_f32 v128, v128, v76, v77
	v_max3_f32 v128, v128, v78, v79
	v_max3_f32 v128, v128, v48, v49
	v_max3_f32 v128, v128, v50, v51
	v_max3_f32 v128, v128, v52, v53
	v_max3_f32 v128, v128, v54, v55
	v_max3_f32 v128, v128, v56, v57
	v_max3_f32 v128, v128, v58, v59
	v_max3_f32 v128, v128, v60, v61
	v_max3_f32 v128, v128, v62, v63
	v_max3_f32 v128, v128, v32, v33
	v_max3_f32 v128, v128, v34, v35
	v_max3_f32 v128, v128, v36, v37
	v_max3_f32 v128, v128, v38, v39
	v_max3_f32 v128, v128, v40, v41
	v_max3_f32 v128, v128, v42, v43
	v_max3_f32 v128, v128, v44, v45
	v_max3_f32 v128, v128, v46, v47
	v_max3_f32 v128, v128, v16, v17
	v_max3_f32 v128, v128, v18, v19
	v_max3_f32 v128, v128, v20, v21
	v_max3_f32 v128, v128, v22, v23
	v_max3_f32 v128, v128, v24, v25
	v_max3_f32 v128, v128, v26, v27
	v_max3_f32 v128, v128, v28, v29
	v_max3_f32 v128, v128, v30, v31
	v_max3_f32 v128, v128, v0, v1
	v_max3_f32 v128, v128, v2, v3
	v_max3_f32 v128, v128, v4, v5
	v_max3_f32 v128, v128, v6, v7
	v_max3_f32 v128, v128, v8, v9
	v_max3_f32 v128, v128, v10, v11
	v_cmp_lt_i32_e32 vcc, v169, v170
	v_max3_f32 v128, v128, v12, v13
	v_max3_f32 v128, v128, v14, v15
	v_cndmask_b32_e32 v129, v168, v169, vcc
	v_lshlrev_b32_e32 v132, 2, v129
	ds_bpermute_b32 v129, v132, v128
	s_lshl_b32 s28, s28, 10
	s_or_b32 s3, s3, s28
	s_waitcnt lgkmcnt(0)
	s_barrier
	s_lshl_b32 s60, s3, 9
	s_add_u32 s60, s6, s60
	s_addc_u32 s61, s7, 0
	v_lshrrev_b32_e32 v245, 6, v212
	v_and_b32_e32 v246, 63, v212
	v_lshrrev_b32_e32 v247, 5, v246
	v_readfirstlane_b32 s62, v245
	v_xor_b32_e32 v246, v246, v247
	v_and_b32_e32 v246, 31, v246
	v_lshlrev_b32_e32 v246, 4, v246
	v_lshlrev_b32_e32 v247, 9, v247
	v_lshl_add_u32 v247, v245, 14, v247
	s_lshl_b32 s62, s62, 14
	s_add_i32 s62, s62, 16
	s_add_i32 m0, s62, 0x0
	v_xor_b32_e32 v245, 0x0, v246
	v_add_u32_e32 v245, v245, v247
	global_load_lds_dwordx4 v245, s[60:61]
	s_add_i32 m0, s62, 0x400
	v_xor_b32_e32 v245, 0x20, v246
	v_add_u32_e32 v245, v245, v247
	v_add_u32_e32 v245, 0x400, v245
	global_load_lds_dwordx4 v245, s[60:61]
	s_add_i32 m0, s62, 0x800
	v_xor_b32_e32 v245, 0x40, v246
	v_add_u32_e32 v245, v245, v247
	v_add_u32_e32 v245, 0x800, v245
	global_load_lds_dwordx4 v245, s[60:61]
	s_add_i32 m0, s62, 0xc00
	v_xor_b32_e32 v245, 0x60, v246
	v_add_u32_e32 v245, v245, v247
	v_add_u32_e32 v245, 0xc00, v245
	global_load_lds_dwordx4 v245, s[60:61]
	s_add_i32 m0, s62, 0x1000
	v_xor_b32_e32 v245, 0x80, v246
	v_add_u32_e32 v245, v245, v247
	v_add_u32_e32 v245, 0x1000, v245
	global_load_lds_dwordx4 v245, s[60:61]
	s_add_i32 m0, s62, 0x1400
	v_xor_b32_e32 v245, 0xa0, v246
	v_add_u32_e32 v245, v245, v247
	v_add_u32_e32 v245, 0x1400, v245
	global_load_lds_dwordx4 v245, s[60:61]
	s_add_i32 m0, s62, 0x1800
	v_xor_b32_e32 v245, 0xc0, v246
	v_add_u32_e32 v245, v245, v247
	v_add_u32_e32 v245, 0x1800, v245
	global_load_lds_dwordx4 v245, s[60:61]
	s_add_i32 m0, s62, 0x1c00
	v_xor_b32_e32 v245, 0xe0, v246
	v_add_u32_e32 v245, v245, v247
	v_add_u32_e32 v245, 0x1c00, v245
	global_load_lds_dwordx4 v245, s[60:61]
	s_add_i32 m0, s62, 0x2000
	v_xor_b32_e32 v245, 0x0, v246
	v_add_u32_e32 v245, v245, v247
	v_add_u32_e32 v245, 0x2000, v245
	global_load_lds_dwordx4 v245, s[60:61]
	s_add_i32 m0, s62, 0x2400
	v_xor_b32_e32 v245, 0x20, v246
	v_add_u32_e32 v245, v245, v247
	v_add_u32_e32 v245, 0x2400, v245
	global_load_lds_dwordx4 v245, s[60:61]
	s_add_i32 m0, s62, 0x2800
	v_xor_b32_e32 v245, 0x40, v246
	v_add_u32_e32 v245, v245, v247
	v_add_u32_e32 v245, 0x2800, v245
	global_load_lds_dwordx4 v245, s[60:61]
	s_add_i32 m0, s62, 0x2c00
	v_xor_b32_e32 v245, 0x60, v246
	v_add_u32_e32 v245, v245, v247
	v_add_u32_e32 v245, 0x2c00, v245
	global_load_lds_dwordx4 v245, s[60:61]
	s_add_i32 m0, s62, 0x3000
	v_xor_b32_e32 v245, 0x80, v246
	v_add_u32_e32 v245, v245, v247
	v_add_u32_e32 v245, 0x3000, v245
	global_load_lds_dwordx4 v245, s[60:61]
; #define LAS __attribute__((address_space(3)))
; DI void attn_prompt_item(const Params& p, int item, ldsp lds, int tid_) {
;     ...
;   float sum = 0.f;
; #pragma unroll
;   for (int kt = 0; kt < 8; ++kt)
; #pragma unroll
;     for (int i = 0; i < 16; ++i) { const float e = __expf(S[kt][i] - mx); S[kt][i] = e; sum += e; }
;   sum += __shfl_xor(sum, 32);
;     ...
;     for (int i = 0; i < 8; ++i) { const int idx = tid + 512 * (hb * 8 + i), d = idx >> 5, c = idx & 31; vp[i] = ld16(mvt + ((size_t)((b * 4 + h) * 256 + d)) * 256 + c * 8); }
; #pragma unroll
;     for (int i = 0; i < 8; ++i) { const int idx = tid + 512 * (hb * 8 + i), d = idx >> 5, c = idx & 31; *(LAS u32x4*)(lds + d * 512 + ((c ^ (d & 15)) * 16)) = vp[i]; }
	s_add_i32 m0, s62, 0x3400
	v_xor_b32_e32 v245, 0xa0, v246
	v_add_u32_e32 v245, v245, v247
	v_add_u32_e32 v245, 0x3400, v245
	global_load_lds_dwordx4 v245, s[60:61]
	s_add_i32 m0, s62, 0x3800
	v_xor_b32_e32 v245, 0xc0, v246
	v_add_u32_e32 v245, v245, v247
	v_add_u32_e32 v245, 0x3800, v245
	global_load_lds_dwordx4 v245, s[60:61]
	s_add_i32 m0, s62, 0x3c00
	v_xor_b32_e32 v245, 0xe0, v246
	v_add_u32_e32 v245, v245, v247
	v_add_u32_e32 v245, 0x3c00, v245
	global_load_lds_dwordx4 v245, s[60:61]
	v_max_f32_e32 v129, v129, v129
	v_max_f32_e32 v134, v128, v129
	v_sub_f32_e32 v112, v112, v134
	v_sub_f32_e32 v113, v113, v134
	v_mul_f32_e32 v112, 0x3fb8aa3b, v112
	v_exp_f32_e32 v133, v112
	v_mul_f32_e32 v112, 0x3fb8aa3b, v113
	v_exp_f32_e32 v135, v112
	v_sub_f32_e32 v112, v114, v134
	v_mul_f32_e32 v112, 0x3fb8aa3b, v112
	v_exp_f32_e32 v136, v112
	v_sub_f32_e32 v112, v115, v134
	v_mul_f32_e32 v112, 0x3fb8aa3b, v112
	v_exp_f32_e32 v137, v112
	v_add_f32_e32 v112, 0, v133
	v_add_f32_e32 v112, v135, v112
	v_add_f32_e32 v112, v136, v112
	v_add_f32_e32 v114, v137, v112
	v_sub_f32_e32 v112, v116, v134
	v_mul_f32_e32 v112, 0x3fb8aa3b, v112
	v_exp_f32_e32 v138, v112
	v_sub_f32_e32 v112, v117, v134
	v_mul_f32_e32 v112, 0x3fb8aa3b, v112
	v_exp_f32_e32 v139, v112
	v_sub_f32_e32 v112, v118, v134
	v_mul_f32_e32 v112, 0x3fb8aa3b, v112
	v_sub_f32_e32 v113, v119, v134
	v_exp_f32_e32 v112, v112
	v_mul_f32_e32 v113, 0x3fb8aa3b, v113
	v_exp_f32_e32 v113, v113
	v_add_f32_e32 v114, v138, v114
	v_add_f32_e32 v114, v139, v114
	v_add_f32_e32 v114, v112, v114
	v_add_f32_e32 v118, v113, v114
	v_sub_f32_e32 v114, v120, v134
	v_mul_f32_e32 v114, 0x3fb8aa3b, v114
	v_sub_f32_e32 v115, v121, v134
	v_exp_f32_e32 v114, v114
	v_mul_f32_e32 v115, 0x3fb8aa3b, v115
	v_sub_f32_e32 v116, v122, v134
	v_exp_f32_e32 v115, v115
	v_mul_f32_e32 v116, 0x3fb8aa3b, v116
	v_sub_f32_e32 v117, v123, v134
	v_exp_f32_e32 v116, v116
	v_mul_f32_e32 v117, 0x3fb8aa3b, v117
	v_exp_f32_e32 v117, v117
	v_add_f32_e32 v118, v114, v118
	v_add_f32_e32 v118, v115, v118
	v_add_f32_e32 v118, v116, v118
	v_add_f32_e32 v122, v117, v118
	v_sub_f32_e32 v118, v124, v134
	v_mul_f32_e32 v118, 0x3fb8aa3b, v118
	v_sub_f32_e32 v119, v125, v134
	v_exp_f32_e32 v118, v118
	v_mul_f32_e32 v119, 0x3fb8aa3b, v119
	v_sub_f32_e32 v120, v126, v134
	v_exp_f32_e32 v119, v119
	v_mul_f32_e32 v120, 0x3fb8aa3b, v120
	v_sub_f32_e32 v121, v127, v134
	v_exp_f32_e32 v120, v120
	v_mul_f32_e32 v121, 0x3fb8aa3b, v121
	v_sub_f32_e32 v96, v96, v134
	v_exp_f32_e32 v121, v121
	v_mul_f32_e32 v96, 0x3fb8aa3b, v96
	v_sub_f32_e32 v97, v97, v134
	v_add_f32_e32 v122, v118, v122
	v_exp_f32_e32 v96, v96
	v_mul_f32_e32 v97, 0x3fb8aa3b, v97
	v_sub_f32_e32 v98, v98, v134
	v_add_f32_e32 v122, v119, v122
	v_exp_f32_e32 v97, v97
	v_mul_f32_e32 v98, 0x3fb8aa3b, v98
	v_sub_f32_e32 v99, v99, v134
	v_add_f32_e32 v122, v120, v122
	v_exp_f32_e32 v98, v98
	v_mul_f32_e32 v99, 0x3fb8aa3b, v99
	v_sub_f32_e32 v100, v100, v134
	v_add_f32_e32 v122, v121, v122
	v_exp_f32_e32 v99, v99
	v_mul_f32_e32 v100, 0x3fb8aa3b, v100
	v_sub_f32_e32 v101, v101, v134
	v_add_f32_e32 v122, v96, v122
	v_exp_f32_e32 v100, v100
	v_mul_f32_e32 v101, 0x3fb8aa3b, v101
	v_sub_f32_e32 v102, v102, v134
	v_add_f32_e32 v122, v97, v122
	v_exp_f32_e32 v101, v101
	v_mul_f32_e32 v102, 0x3fb8aa3b, v102
	v_sub_f32_e32 v103, v103, v134
	v_add_f32_e32 v122, v98, v122
	v_exp_f32_e32 v102, v102
	v_mul_f32_e32 v103, 0x3fb8aa3b, v103
	v_sub_f32_e32 v104, v104, v134
	v_add_f32_e32 v122, v99, v122
	v_exp_f32_e32 v103, v103
	v_mul_f32_e32 v104, 0x3fb8aa3b, v104
	v_sub_f32_e32 v105, v105, v134
	v_sub_f32_e32 v108, v108, v134
	v_add_f32_e32 v122, v100, v122
	v_exp_f32_e32 v104, v104
	v_mul_f32_e32 v105, 0x3fb8aa3b, v105
	v_sub_f32_e32 v106, v106, v134
	v_mul_f32_e32 v108, 0x3fb8aa3b, v108
	v_add_f32_e32 v122, v101, v122
	v_exp_f32_e32 v105, v105
	v_mul_f32_e32 v106, 0x3fb8aa3b, v106
	v_sub_f32_e32 v107, v107, v134
	v_exp_f32_e32 v128, v108
	v_sub_f32_e32 v108, v109, v134
	v_add_f32_e32 v122, v102, v122
	v_exp_f32_e32 v106, v106
	v_mul_f32_e32 v107, 0x3fb8aa3b, v107
	v_mul_f32_e32 v108, 0x3fb8aa3b, v108
	v_add_f32_e32 v122, v103, v122
	v_exp_f32_e32 v107, v107
	v_exp_f32_e32 v129, v108
	v_sub_f32_e32 v108, v110, v134
	v_add_f32_e32 v122, v104, v122
	v_mul_f32_e32 v108, 0x3fb8aa3b, v108
	v_add_f32_e32 v122, v105, v122
	v_exp_f32_e32 v130, v108
	v_sub_f32_e32 v108, v111, v134
	v_add_f32_e32 v122, v106, v122
	v_mul_f32_e32 v108, 0x3fb8aa3b, v108
	v_sub_f32_e32 v80, v80, v134
	v_add_f32_e32 v122, v107, v122
	v_exp_f32_e32 v131, v108
	v_mul_f32_e32 v80, 0x3fb8aa3b, v80
	v_sub_f32_e32 v81, v81, v134
	v_add_f32_e32 v108, v128, v122
	v_exp_f32_e32 v80, v80
	v_mul_f32_e32 v81, 0x3fb8aa3b, v81
	v_sub_f32_e32 v82, v82, v134
	v_add_f32_e32 v108, v129, v108
	v_exp_f32_e32 v81, v81
	v_mul_f32_e32 v82, 0x3fb8aa3b, v82
	v_sub_f32_e32 v83, v83, v134
	v_add_f32_e32 v108, v130, v108
	v_exp_f32_e32 v82, v82
	v_mul_f32_e32 v83, 0x3fb8aa3b, v83
	v_sub_f32_e32 v84, v84, v134
	v_add_f32_e32 v108, v131, v108
	v_exp_f32_e32 v83, v83
	v_mul_f32_e32 v84, 0x3fb8aa3b, v84
	v_sub_f32_e32 v85, v85, v134
	v_add_f32_e32 v108, v80, v108
	v_exp_f32_e32 v84, v84
	v_mul_f32_e32 v85, 0x3fb8aa3b, v85
	v_sub_f32_e32 v86, v86, v134
	v_add_f32_e32 v108, v81, v108
	v_exp_f32_e32 v85, v85
	v_mul_f32_e32 v86, 0x3fb8aa3b, v86
	v_sub_f32_e32 v87, v87, v134
	v_add_f32_e32 v108, v82, v108
	v_exp_f32_e32 v86, v86
	v_mul_f32_e32 v87, 0x3fb8aa3b, v87
	v_sub_f32_e32 v88, v88, v134
	v_add_f32_e32 v108, v83, v108
	v_exp_f32_e32 v87, v87
	v_mul_f32_e32 v88, 0x3fb8aa3b, v88
	v_sub_f32_e32 v89, v89, v134
	v_add_f32_e32 v108, v84, v108
	v_exp_f32_e32 v88, v88
	v_mul_f32_e32 v89, 0x3fb8aa3b, v89
; DI void attn_prompt_item(const Params& p, int item, ldsp lds, int tid_) {
;     ...
;   float sum = 0.f;
; #pragma unroll
;   for (int kt = 0; kt < 8; ++kt)
; #pragma unroll
;     for (int i = 0; i < 16; ++i) { const float e = __expf(S[kt][i] - mx); S[kt][i] = e; sum += e; }
	v_sub_f32_e32 v90, v90, v134
	v_add_f32_e32 v108, v85, v108
	v_exp_f32_e32 v89, v89
	v_mul_f32_e32 v90, 0x3fb8aa3b, v90
	v_sub_f32_e32 v91, v91, v134
	v_add_f32_e32 v108, v86, v108
	v_exp_f32_e32 v90, v90
	v_mul_f32_e32 v91, 0x3fb8aa3b, v91
	v_sub_f32_e32 v92, v92, v134
	v_add_f32_e32 v108, v87, v108
	v_exp_f32_e32 v91, v91
	v_mul_f32_e32 v92, 0x3fb8aa3b, v92
	v_sub_f32_e32 v93, v93, v134
	v_add_f32_e32 v108, v88, v108
	v_exp_f32_e32 v92, v92
	v_mul_f32_e32 v93, 0x3fb8aa3b, v93
	v_sub_f32_e32 v94, v94, v134
	v_add_f32_e32 v108, v89, v108
	v_exp_f32_e32 v93, v93
	v_mul_f32_e32 v94, 0x3fb8aa3b, v94
	v_sub_f32_e32 v95, v95, v134
	v_add_f32_e32 v108, v90, v108
	v_exp_f32_e32 v94, v94
	v_mul_f32_e32 v95, 0x3fb8aa3b, v95
	v_sub_f32_e32 v64, v64, v134
	v_add_f32_e32 v108, v91, v108
	v_exp_f32_e32 v95, v95
	v_mul_f32_e32 v64, 0x3fb8aa3b, v64
	v_sub_f32_e32 v65, v65, v134
	v_add_f32_e32 v108, v92, v108
	v_exp_f32_e32 v64, v64
	v_mul_f32_e32 v65, 0x3fb8aa3b, v65
	v_sub_f32_e32 v66, v66, v134
	v_add_f32_e32 v108, v93, v108
	v_exp_f32_e32 v65, v65
	v_mul_f32_e32 v66, 0x3fb8aa3b, v66
	v_sub_f32_e32 v67, v67, v134
	v_add_f32_e32 v108, v94, v108
	v_exp_f32_e32 v66, v66
	v_mul_f32_e32 v67, 0x3fb8aa3b, v67
	v_sub_f32_e32 v68, v68, v134
	v_add_f32_e32 v108, v95, v108
	v_exp_f32_e32 v67, v67
	v_mul_f32_e32 v68, 0x3fb8aa3b, v68
	v_sub_f32_e32 v69, v69, v134
	v_add_f32_e32 v108, v64, v108
	v_exp_f32_e32 v68, v68
	v_mul_f32_e32 v69, 0x3fb8aa3b, v69
	v_sub_f32_e32 v70, v70, v134
	v_add_f32_e32 v108, v65, v108
	v_exp_f32_e32 v69, v69
	v_mul_f32_e32 v70, 0x3fb8aa3b, v70
	v_sub_f32_e32 v71, v71, v134
	v_add_f32_e32 v108, v66, v108
	v_exp_f32_e32 v70, v70
	v_mul_f32_e32 v71, 0x3fb8aa3b, v71
	v_sub_f32_e32 v72, v72, v134
	v_add_f32_e32 v108, v67, v108
	v_exp_f32_e32 v71, v71
	v_mul_f32_e32 v72, 0x3fb8aa3b, v72
	v_sub_f32_e32 v73, v73, v134
	v_add_f32_e32 v108, v68, v108
	v_exp_f32_e32 v72, v72
	v_mul_f32_e32 v73, 0x3fb8aa3b, v73
	v_sub_f32_e32 v74, v74, v134
	v_add_f32_e32 v108, v69, v108
	v_exp_f32_e32 v73, v73
	v_mul_f32_e32 v74, 0x3fb8aa3b, v74
	v_sub_f32_e32 v75, v75, v134
	v_add_f32_e32 v108, v70, v108
	v_exp_f32_e32 v74, v74
	v_mul_f32_e32 v75, 0x3fb8aa3b, v75
	v_sub_f32_e32 v76, v76, v134
	v_add_f32_e32 v108, v71, v108
	v_exp_f32_e32 v75, v75
	v_mul_f32_e32 v76, 0x3fb8aa3b, v76
	v_sub_f32_e32 v77, v77, v134
	v_add_f32_e32 v108, v72, v108
	v_exp_f32_e32 v76, v76
	v_mul_f32_e32 v77, 0x3fb8aa3b, v77
	v_sub_f32_e32 v78, v78, v134
	v_add_f32_e32 v108, v73, v108
	v_exp_f32_e32 v77, v77
	v_mul_f32_e32 v78, 0x3fb8aa3b, v78
	v_sub_f32_e32 v79, v79, v134
	v_add_f32_e32 v108, v74, v108
	v_exp_f32_e32 v78, v78
	v_mul_f32_e32 v79, 0x3fb8aa3b, v79
	v_sub_f32_e32 v48, v48, v134
	v_add_f32_e32 v108, v75, v108
	v_exp_f32_e32 v79, v79
	v_mul_f32_e32 v48, 0x3fb8aa3b, v48
	v_sub_f32_e32 v49, v49, v134
	v_add_f32_e32 v108, v76, v108
	v_exp_f32_e32 v48, v48
	v_mul_f32_e32 v49, 0x3fb8aa3b, v49
	v_sub_f32_e32 v50, v50, v134
	v_add_f32_e32 v108, v77, v108
	v_exp_f32_e32 v49, v49
	v_mul_f32_e32 v50, 0x3fb8aa3b, v50
	v_sub_f32_e32 v51, v51, v134
	v_add_f32_e32 v108, v78, v108
	v_exp_f32_e32 v50, v50
	v_mul_f32_e32 v51, 0x3fb8aa3b, v51
	v_sub_f32_e32 v52, v52, v134
	v_add_f32_e32 v108, v79, v108
	v_exp_f32_e32 v51, v51
	v_mul_f32_e32 v52, 0x3fb8aa3b, v52
	v_sub_f32_e32 v53, v53, v134
	v_add_f32_e32 v108, v48, v108
	v_exp_f32_e32 v52, v52
	v_mul_f32_e32 v53, 0x3fb8aa3b, v53
	v_sub_f32_e32 v54, v54, v134
	v_add_f32_e32 v108, v49, v108
	v_exp_f32_e32 v53, v53
	v_mul_f32_e32 v54, 0x3fb8aa3b, v54
	v_sub_f32_e32 v55, v55, v134
	v_add_f32_e32 v108, v50, v108
	v_exp_f32_e32 v54, v54
	v_mul_f32_e32 v55, 0x3fb8aa3b, v55
	v_sub_f32_e32 v56, v56, v134
	v_add_f32_e32 v108, v51, v108
	v_exp_f32_e32 v55, v55
	v_mul_f32_e32 v56, 0x3fb8aa3b, v56
	v_sub_f32_e32 v57, v57, v134
	v_add_f32_e32 v108, v52, v108
	v_exp_f32_e32 v56, v56
	v_mul_f32_e32 v57, 0x3fb8aa3b, v57
	v_sub_f32_e32 v58, v58, v134
	v_add_f32_e32 v108, v53, v108
	v_exp_f32_e32 v57, v57
	v_mul_f32_e32 v58, 0x3fb8aa3b, v58
	v_sub_f32_e32 v59, v59, v134
	v_add_f32_e32 v108, v54, v108
	v_exp_f32_e32 v58, v58
	v_mul_f32_e32 v59, 0x3fb8aa3b, v59
	v_sub_f32_e32 v60, v60, v134
	v_add_f32_e32 v108, v55, v108
	v_exp_f32_e32 v59, v59
	v_mul_f32_e32 v60, 0x3fb8aa3b, v60
	v_sub_f32_e32 v61, v61, v134
	v_add_f32_e32 v108, v56, v108
	v_exp_f32_e32 v60, v60
	v_mul_f32_e32 v61, 0x3fb8aa3b, v61
	v_sub_f32_e32 v62, v62, v134
	v_add_f32_e32 v108, v57, v108
	v_exp_f32_e32 v61, v61
	v_mul_f32_e32 v62, 0x3fb8aa3b, v62
	v_sub_f32_e32 v63, v63, v134
	v_sub_f32_e32 v36, v36, v134
	v_add_f32_e32 v108, v58, v108
	v_exp_f32_e32 v62, v62
	v_mul_f32_e32 v63, 0x3fb8aa3b, v63
	v_sub_f32_e32 v32, v32, v134
	v_mul_f32_e32 v36, 0x3fb8aa3b, v36
	v_add_f32_e32 v108, v59, v108
	v_exp_f32_e32 v63, v63
	v_mul_f32_e32 v32, 0x3fb8aa3b, v32
	v_sub_f32_e32 v33, v33, v134
	v_exp_f32_e32 v152, v36
	v_sub_f32_e32 v36, v37, v134
	v_sub_f32_e32 v37, v40, v134
	v_add_f32_e32 v108, v60, v108
	v_exp_f32_e32 v32, v32
	v_mul_f32_e32 v33, 0x3fb8aa3b, v33
	v_sub_f32_e32 v34, v34, v134
	v_mul_f32_e32 v37, 0x3fb8aa3b, v37
	v_add_f32_e32 v108, v61, v108
	v_exp_f32_e32 v33, v33
	v_mul_f32_e32 v34, 0x3fb8aa3b, v34
	v_sub_f32_e32 v35, v35, v134
	v_exp_f32_e32 v156, v37
	v_sub_f32_e32 v37, v41, v134
	v_add_f32_e32 v108, v62, v108
	v_exp_f32_e32 v34, v34
	v_mul_f32_e32 v35, 0x3fb8aa3b, v35
	v_mul_f32_e32 v36, 0x3fb8aa3b, v36
	v_mul_f32_e32 v37, 0x3fb8aa3b, v37
	v_add_f32_e32 v108, v63, v108
	v_exp_f32_e32 v35, v35
	v_exp_f32_e32 v153, v36
	v_sub_f32_e32 v36, v38, v134
	v_exp_f32_e32 v157, v37
	v_sub_f32_e32 v37, v42, v134
	v_add_f32_e32 v108, v32, v108
	v_mul_f32_e32 v36, 0x3fb8aa3b, v36
; #define LAS __attribute__((address_space(3)))
; DI unsigned pk2(float lo, float hi) { f32x2 v = {lo, hi}; return __builtin_bit_cast(unsigned, __builtin_convertvector(v, bf16x2v)); }
; DI void attn_prompt_item(const Params& p, int item, ldsp lds, int tid_) {
;     ...
;   float sum = 0.f;
; #pragma unroll
;   for (int kt = 0; kt < 8; ++kt)
; #pragma unroll
;     for (int i = 0; i < 16; ++i) { const float e = __expf(S[kt][i] - mx); S[kt][i] = e; sum += e; }
;   sum += __shfl_xor(sum, 32);
;   const float inv = 1.f / sum;
;   bf16x8 pb[8][2];
; #pragma unroll
;   for (int kt = 0; kt < 8; ++kt)
; #pragma unroll
;     for (int s = 0; s < 2; ++s) {
;       u32x4 pw; pw.x = pk2(S[kt][8 * s], S[kt][8 * s + 1]); pw.y = pk2(S[kt][8 * s + 2], S[kt][8 * s + 3]); pw.z = pk2(S[kt][8 * s + 4], S[kt][8 * s + 5]); pw.w = pk2(S[kt][8 * s + 6], S[kt][8 * s + 7]);
;       pb[kt][s] = __builtin_bit_cast(bf16x8, pw);
;     }
;   __syncthreads();
; #pragma unroll
;   for (int hb = 0; hb < 2; ++hb) {
;     u32x4 vp[8];
; #pragma unroll
;     for (int i = 0; i < 8; ++i) { const int idx = tid + 512 * (hb * 8 + i), d = idx >> 5, c = idx & 31; vp[i] = ld16(mvt + ((size_t)((b * 4 + h) * 256 + d)) * 256 + c * 8); }
; #pragma unroll
;     for (int i = 0; i < 8; ++i) { const int idx = tid + 512 * (hb * 8 + i), d = idx >> 5, c = idx & 31; *(LAS u32x4*)(lds + d * 512 + ((c ^ (d & 15)) * 16)) = vp[i]; }
;   }
;   __syncthreads();
	v_mul_f32_e32 v37, 0x3fb8aa3b, v37
	v_add_f32_e32 v108, v33, v108
	v_exp_f32_e32 v154, v36
	v_sub_f32_e32 v36, v39, v134
	v_exp_f32_e32 v158, v37
	v_sub_f32_e32 v37, v43, v134
	v_sub_f32_e32 v16, v16, v134
	v_add_f32_e32 v108, v34, v108
	v_mul_f32_e32 v36, 0x3fb8aa3b, v36
	v_mul_f32_e32 v37, 0x3fb8aa3b, v37
	v_mul_f32_e32 v16, 0x3fb8aa3b, v16
	v_add_f32_e32 v108, v35, v108
	v_exp_f32_e32 v155, v36
	v_exp_f32_e32 v159, v37
	v_sub_f32_e32 v37, v44, v134
	v_exp_f32_e32 v210, v16
	v_sub_f32_e32 v16, v17, v134
	v_sub_f32_e32 v17, v20, v134
	v_add_f32_e32 v36, v152, v108
	v_mul_f32_e32 v37, 0x3fb8aa3b, v37
	v_mul_f32_e32 v17, 0x3fb8aa3b, v17
	v_add_f32_e32 v36, v153, v36
	v_exp_f32_e32 v166, v37
	v_sub_f32_e32 v37, v45, v134
	v_exp_f32_e32 v216, v17
	v_sub_f32_e32 v17, v21, v134
	v_add_f32_e32 v36, v154, v36
	v_mul_f32_e32 v37, 0x3fb8aa3b, v37
	v_mul_f32_e32 v17, 0x3fb8aa3b, v17
	v_add_f32_e32 v36, v155, v36
	v_exp_f32_e32 v167, v37
	v_sub_f32_e32 v37, v46, v134
	v_exp_f32_e32 v217, v17
	v_sub_f32_e32 v17, v22, v134
	v_add_f32_e32 v36, v156, v36
	v_mul_f32_e32 v37, 0x3fb8aa3b, v37
	v_mul_f32_e32 v17, 0x3fb8aa3b, v17
	v_add_f32_e32 v36, v157, v36
	v_exp_f32_e32 v208, v37
	v_sub_f32_e32 v37, v47, v134
	v_exp_f32_e32 v218, v17
	v_sub_f32_e32 v17, v23, v134
	v_add_f32_e32 v36, v158, v36
	v_mul_f32_e32 v37, 0x3fb8aa3b, v37
	v_mul_f32_e32 v16, 0x3fb8aa3b, v16
	v_mul_f32_e32 v17, 0x3fb8aa3b, v17
	v_add_f32_e32 v36, v159, v36
	v_exp_f32_e32 v209, v37
	v_exp_f32_e32 v211, v16
	v_sub_f32_e32 v16, v18, v134
	v_exp_f32_e32 v219, v17
	v_sub_f32_e32 v17, v24, v134
	v_add_f32_e32 v36, v166, v36
	v_mul_f32_e32 v16, 0x3fb8aa3b, v16
	v_mul_f32_e32 v17, 0x3fb8aa3b, v17
	v_add_f32_e32 v36, v167, v36
	v_exp_f32_e32 v214, v16
	v_sub_f32_e32 v16, v19, v134
	v_exp_f32_e32 v220, v17
	v_sub_f32_e32 v17, v25, v134
	v_add_f32_e32 v36, v208, v36
	v_mul_f32_e32 v16, 0x3fb8aa3b, v16
	v_mul_f32_e32 v17, 0x3fb8aa3b, v17
	v_add_f32_e32 v36, v209, v36
	v_exp_f32_e32 v215, v16
	v_exp_f32_e32 v221, v17
	v_sub_f32_e32 v17, v26, v134
	v_add_f32_e32 v16, v210, v36
	v_mul_f32_e32 v17, 0x3fb8aa3b, v17
	v_add_f32_e32 v16, v211, v16
	v_exp_f32_e32 v222, v17
	v_sub_f32_e32 v17, v27, v134
	v_sub_f32_e32 v0, v0, v134
	v_add_f32_e32 v16, v214, v16
	v_mul_f32_e32 v17, 0x3fb8aa3b, v17
	v_mul_f32_e32 v0, 0x3fb8aa3b, v0
	v_add_f32_e32 v16, v215, v16
	v_exp_f32_e32 v223, v17
	v_sub_f32_e32 v17, v28, v134
	v_exp_f32_e32 v228, v0
	v_sub_f32_e32 v0, v1, v134
	v_sub_f32_e32 v1, v4, v134
	v_add_f32_e32 v16, v216, v16
	v_mul_f32_e32 v17, 0x3fb8aa3b, v17
	v_mul_f32_e32 v1, 0x3fb8aa3b, v1
	v_add_f32_e32 v16, v217, v16
	v_exp_f32_e32 v224, v17
	v_sub_f32_e32 v17, v29, v134
	v_exp_f32_e32 v232, v1
	v_sub_f32_e32 v1, v5, v134
	v_add_f32_e32 v16, v218, v16
	v_mul_f32_e32 v17, 0x3fb8aa3b, v17
	v_mul_f32_e32 v1, 0x3fb8aa3b, v1
	v_add_f32_e32 v16, v219, v16
	v_exp_f32_e32 v225, v17
	v_sub_f32_e32 v17, v30, v134
	v_exp_f32_e32 v233, v1
	v_sub_f32_e32 v1, v6, v134
	v_add_f32_e32 v16, v220, v16
	v_mul_f32_e32 v17, 0x3fb8aa3b, v17
	v_mul_f32_e32 v1, 0x3fb8aa3b, v1
	v_add_f32_e32 v16, v221, v16
	v_exp_f32_e32 v226, v17
	v_sub_f32_e32 v17, v31, v134
	v_exp_f32_e32 v234, v1
	v_sub_f32_e32 v1, v7, v134
	v_add_f32_e32 v16, v222, v16
	v_mul_f32_e32 v17, 0x3fb8aa3b, v17
	v_mul_f32_e32 v0, 0x3fb8aa3b, v0
	v_mul_f32_e32 v1, 0x3fb8aa3b, v1
	v_add_f32_e32 v16, v223, v16
	v_exp_f32_e32 v227, v17
	v_exp_f32_e32 v229, v0
	v_sub_f32_e32 v0, v2, v134
	v_exp_f32_e32 v235, v1
	v_sub_f32_e32 v1, v8, v134
	v_add_f32_e32 v16, v224, v16
	v_mul_f32_e32 v0, 0x3fb8aa3b, v0
	v_mul_f32_e32 v1, 0x3fb8aa3b, v1
	v_add_f32_e32 v16, v225, v16
	v_exp_f32_e32 v230, v0
	v_sub_f32_e32 v0, v3, v134
	v_exp_f32_e32 v236, v1
	v_sub_f32_e32 v1, v9, v134
	v_add_f32_e32 v16, v226, v16
	v_mul_f32_e32 v0, 0x3fb8aa3b, v0
	v_mul_f32_e32 v1, 0x3fb8aa3b, v1
	v_add_f32_e32 v16, v227, v16
	v_exp_f32_e32 v231, v0
	v_exp_f32_e32 v237, v1
	v_sub_f32_e32 v1, v10, v134
	v_add_f32_e32 v0, v228, v16
	v_mul_f32_e32 v1, 0x3fb8aa3b, v1
	v_add_f32_e32 v0, v229, v0
	v_exp_f32_e32 v238, v1
	v_sub_f32_e32 v1, v11, v134
	v_add_f32_e32 v0, v230, v0
	v_mul_f32_e32 v1, 0x3fb8aa3b, v1
	v_add_f32_e32 v0, v231, v0
	v_exp_f32_e32 v239, v1
	v_sub_f32_e32 v1, v12, v134
	v_add_f32_e32 v0, v232, v0
	v_mul_f32_e32 v1, 0x3fb8aa3b, v1
	v_add_f32_e32 v0, v233, v0
	v_exp_f32_e32 v240, v1
	v_sub_f32_e32 v1, v13, v134
	v_add_f32_e32 v0, v234, v0
	v_mul_f32_e32 v1, 0x3fb8aa3b, v1
	v_add_f32_e32 v0, v235, v0
	v_exp_f32_e32 v241, v1
	v_sub_f32_e32 v1, v14, v134
	v_add_f32_e32 v0, v236, v0
	v_mul_f32_e32 v1, 0x3fb8aa3b, v1
	v_add_f32_e32 v0, v237, v0
	v_exp_f32_e32 v242, v1
	v_sub_f32_e32 v1, v15, v134
	v_add_f32_e32 v0, v238, v0
	v_mul_f32_e32 v1, 0x3fb8aa3b, v1
	v_add_f32_e32 v0, v239, v0
	v_exp_f32_e32 v243, v1
	v_add_f32_e32 v0, v240, v0
	v_add_f32_e32 v0, v241, v0
	v_add_f32_e32 v0, v242, v0
	v_add_f32_e32 v0, v243, v0
	ds_bpermute_b32 v1, v132, v0
	s_waitcnt lgkmcnt(0)
	v_add_f32_e32 v244, v0, v1
	v_cvt_pk_bf16_f32 v108, v133, v135
	v_cvt_pk_bf16_f32 v109, v136, v137
	v_cvt_pk_bf16_f32 v110, v138, v139
	v_div_scale_f32 v12, s[28:29], v244, v244, 1.0
	v_rcp_f32_e32 v13, v12
	v_and_b32_e32 v146, 0xf0, v174
	v_bitop3_b32 v139, v174, 16, v171 bitop3:0x6c
	v_fma_f32 v0, -v12, v13, 1.0
	v_add3_u32 v14, v173, v146, v160
	v_add3_u32 v15, v173, v139, v160
	v_fmac_f32_e32 v13, v0, v13
	s_waitcnt vmcnt(0)
	s_waitcnt lgkmcnt(0)
	s_barrier
; #define LAS __attribute__((address_space(3)))
; DI unsigned pk2(float lo, float hi) { f32x2 v = {lo, hi}; return __builtin_bit_cast(unsigned, __builtin_convertvector(v, bf16x2v)); }
; DI void attn_prompt_item(const Params& p, int item, ldsp lds, int tid_) {
;     ...
;   bf16x8 pb[8][2];
; #pragma unroll
;   for (int kt = 0; kt < 8; ++kt)
; #pragma unroll
;     for (int s = 0; s < 2; ++s) {
;       u32x4 pw; pw.x = pk2(S[kt][8 * s], S[kt][8 * s + 1]); pw.y = pk2(S[kt][8 * s + 2], S[kt][8 * s + 3]); pw.z = pk2(S[kt][8 * s + 4], S[kt][8 * s + 5]); pw.w = pk2(S[kt][8 * s + 6], S[kt][8 * s + 7]);
;       pb[kt][s] = __builtin_bit_cast(bf16x8, pw);
;     }
;   __syncthreads();
; #pragma unroll
;   for (int hb = 0; hb < 2; ++hb) {
;     u32x4 vp[8];
; #pragma unroll
;     for (int i = 0; i < 8; ++i) { const int idx = tid + 512 * (hb * 8 + i), d = idx >> 5, c = idx & 31; vp[i] = ld16(mvt + ((size_t)((b * 4 + h) * 256 + d)) * 256 + c * 8); }
; #pragma unroll
;     for (int i = 0; i < 8; ++i) { const int idx = tid + 512 * (hb * 8 + i), d = idx >> 5, c = idx & 31; *(LAS u32x4*)(lds + d * 512 + ((c ^ (d & 15)) * 16)) = vp[i]; }
;   }
;   __syncthreads();
; #pragma unroll
;   for (int dh = 0; dh < 2; ++dh) {
;     f32x16 O[4];
; #pragma unroll
;     for (int dt = 0; dt < 4; ++dt)
; #pragma unroll
;       for (int i = 0; i < 16; ++i) O[dt][i] = 0.f;
;     {
;       u32x2 va[4][2], vb[4][2];
;     ...
; #pragma unroll
;       for (int dt = 0; dt < 4; ++dt) { va[dt][0] = *(const LAS u32x2*)VF_ADDR(0, dt, 0); va[dt][1] = *(const LAS u32x2*)VF_ADDR(0, dt, 1); }
; #pragma unroll
;       for (int gi = 0; gi < 16; ++gi) {
;         if (gi + 1 < 16) {
; #pragma unroll
;           for (int dt = 0; dt < 4; ++dt) {
;             if (gi & 1) { va[dt][0] = *(const LAS u32x2*)VF_ADDR(gi + 1, dt, 0); va[dt][1] = *(const LAS u32x2*)VF_ADDR(gi + 1, dt, 1); }
;             else { vb[dt][0] = *(const LAS u32x2*)VF_ADDR(gi + 1, dt, 0); vb[dt][1] = *(const LAS u32x2*)VF_ADDR(gi + 1, dt, 1); } } }
; #pragma unroll
;         for (int dt = 0; dt < 4; ++dt) { const u32x2 lo = (gi & 1) ? vb[dt][0] : va[dt][0], hi = (gi & 1) ? vb[dt][1] : va[dt][1];
;           u32x4 vw; vw.x = lo.x; vw.y = lo.y; vw.z = hi.x; vw.w = hi.y;
;           O[dt] = __builtin_amdgcn_mfma_f32_32x32x16_bf16(__builtin_bit_cast(bf16x8, vw), pb[gi >> 1][gi & 1], O[dt], 0, 0, 0); }
	ds_read2st64_b64 v[0:3], v14 offset1:32
	ds_read2st64_b64 v[4:7], v15 offset1:32
	v_div_scale_f32 v16, vcc, 1.0, v244, 1.0
	v_cvt_pk_bf16_f32 v111, v112, v113
	s_waitcnt lgkmcnt(1)
	v_mov_b32_e32 v8, v0
	v_mov_b32_e32 v9, v1
	s_waitcnt lgkmcnt(0)
	v_mov_b32_e32 v10, v4
	v_mov_b32_e32 v11, v5
	v_mul_f32_e32 v0, v16, v13
	v_fma_f32 v1, -v12, v0, v16
	v_fmac_f32_e32 v0, v1, v13
	v_fma_f32 v1, -v12, v0, v16
	v_cvt_pk_bf16_f32 v125, v116, v117
	v_cvt_pk_bf16_f32 v116, v104, v105
	v_cvt_pk_bf16_f32 v117, v106, v107
	v_cvt_pk_bf16_f32 v104, v88, v89
	v_cvt_pk_bf16_f32 v105, v90, v91
	v_cvt_pk_bf16_f32 v106, v92, v93
	v_cvt_pk_bf16_f32 v107, v94, v95
	v_cvt_pk_bf16_f32 v92, v48, v49
	v_cvt_pk_bf16_f32 v93, v50, v51
	v_cvt_pk_bf16_f32 v94, v52, v53
	v_cvt_pk_bf16_f32 v95, v54, v55
	v_cvt_pk_bf16_f32 v88, v56, v57
	v_cvt_pk_bf16_f32 v89, v58, v59
	v_cvt_pk_bf16_f32 v90, v60, v61
	v_cvt_pk_bf16_f32 v91, v62, v63
	v_mfma_f32_32x32x16_bf16 v[48:63], v[8:11], v[108:111], 0
	ds_read2st64_b64 v[8:11], v14 offset0:64 offset1:96
	v_mov_b32_e32 v4, v2
	v_mov_b32_e32 v5, v3
	v_div_fmas_f32 v12, v1, v13, v0
	ds_read2st64_b64 v[0:3], v15 offset0:64 offset1:96
	v_cvt_pk_bf16_f32 v126, v118, v119
	v_cvt_pk_bf16_f32 v118, v128, v129
	v_lshlrev_b32_e32 v129, 4, v175
	v_xor_b32_e32 v147, 32, v129
	v_xor_b32_e32 v148, 48, v129
	v_cvt_pk_bf16_f32 v112, v80, v81
	v_cvt_pk_bf16_f32 v81, v158, v159
	v_add3_u32 v149, v173, v147, v160
	v_add3_u32 v158, v173, v148, v160
	v_cvt_pk_bf16_f32 v124, v114, v115
	v_cvt_pk_bf16_f32 v119, v130, v131
	v_cvt_pk_bf16_f32 v115, v86, v87
	v_cvt_pk_bf16_f32 v86, v152, v153
	ds_read2st64_b64 v[130:133], v149 offset1:32
	ds_read2st64_b64 v[134:137], v158 offset1:32
	ds_read2st64_b64 v[140:143], v149 offset0:64 offset1:96
	ds_read2st64_b64 v[150:153], v158 offset0:64 offset1:96
	v_cvt_pk_bf16_f32 v114, v84, v85
	v_cvt_pk_bf16_f32 v84, v32, v33
	v_cvt_pk_bf16_f32 v85, v34, v35
	v_mfma_f32_32x32x16_bf16 v[32:47], v[4:7], v[108:111], 0
	s_waitcnt lgkmcnt(5)
	v_mov_b32_e32 v4, v8
	v_mov_b32_e32 v5, v9
	s_waitcnt lgkmcnt(4)
	v_mov_b32_e32 v6, v0
	v_mov_b32_e32 v7, v1
	v_mov_b32_e32 v0, v10
	v_mov_b32_e32 v1, v11
	v_cvt_pk_bf16_f32 v127, v120, v121
	v_cvt_pk_bf16_f32 v120, v96, v97
	v_cvt_pk_bf16_f32 v121, v98, v99
	v_cvt_pk_bf16_f32 v122, v100, v101
	v_cvt_pk_bf16_f32 v123, v102, v103
	v_cvt_pk_bf16_f32 v113, v82, v83
	v_cvt_pk_bf16_f32 v100, v64, v65
	v_cvt_pk_bf16_f32 v101, v66, v67
	v_cvt_pk_bf16_f32 v102, v68, v69
	v_cvt_pk_bf16_f32 v103, v70, v71
	v_cvt_pk_bf16_f32 v96, v72, v73
	v_cvt_pk_bf16_f32 v97, v74, v75
	v_cvt_pk_bf16_f32 v98, v76, v77
	v_cvt_pk_bf16_f32 v99, v78, v79
	v_cvt_pk_bf16_f32 v87, v154, v155
	v_cvt_pk_bf16_f32 v80, v156, v157
	v_cvt_pk_bf16_f32 v82, v166, v167
	v_cvt_pk_bf16_f32 v83, v208, v209
	v_cvt_pk_bf16_f32 v76, v210, v211
	v_cvt_pk_bf16_f32 v77, v214, v215
	v_cvt_pk_bf16_f32 v78, v216, v217
	v_cvt_pk_bf16_f32 v79, v218, v219
	v_cvt_pk_bf16_f32 v72, v220, v221
	v_cvt_pk_bf16_f32 v73, v222, v223
	v_cvt_pk_bf16_f32 v74, v224, v225
	v_cvt_pk_bf16_f32 v75, v226, v227
	v_cvt_pk_bf16_f32 v68, v228, v229
	v_cvt_pk_bf16_f32 v69, v230, v231
	v_cvt_pk_bf16_f32 v70, v232, v233
	v_cvt_pk_bf16_f32 v71, v234, v235
	v_cvt_pk_bf16_f32 v64, v236, v237
	v_cvt_pk_bf16_f32 v65, v238, v239
	v_cvt_pk_bf16_f32 v66, v240, v241
	v_cvt_pk_bf16_f32 v67, v242, v243
	v_div_fixup_f32 v128, v12, v244, 1.0
	v_mfma_f32_32x32x16_bf16 v[16:31], v[4:7], v[108:111], 0
	v_mfma_f32_32x32x16_bf16 v[0:15], v[0:3], v[108:111], 0
	s_waitcnt lgkmcnt(3)
	v_mov_b32_e32 v154, v130
	v_mov_b32_e32 v155, v131
	s_waitcnt lgkmcnt(2)
	v_mov_b32_e32 v156, v134
	v_mov_b32_e32 v157, v135
	v_mov_b32_e32 v134, v132
	v_mov_b32_e32 v135, v133
	s_waitcnt lgkmcnt(1)
	v_mov_b32_e32 v130, v140
	v_mov_b32_e32 v131, v141
	s_waitcnt lgkmcnt(0)
	v_mov_b32_e32 v132, v150
	v_mov_b32_e32 v133, v151
	v_xor_b32_e32 v144, 64, v129
	v_xor_b32_e32 v145, 0x50, v129
	v_add3_u32 v159, v173, v144, v160
	v_add3_u32 v182, v173, v145, v160
	v_mfma_f32_32x32x16_bf16 v[48:63], v[154:157], v[124:127], v[48:63]
	v_mov_b32_e32 v150, v142
	v_mov_b32_e32 v151, v143
	v_mfma_f32_32x32x16_bf16 v[32:47], v[134:137], v[124:127], v[32:47]
	v_mfma_f32_32x32x16_bf16 v[16:31], v[130:133], v[124:127], v[16:31]
	ds_read2st64_b64 v[130:133], v159 offset1:32
	ds_read2st64_b64 v[134:137], v182 offset1:32
	ds_read2st64_b64 v[154:157], v159 offset0:64 offset1:96
	ds_read2st64_b64 v[164:167], v182 offset0:64 offset1:96
	v_mfma_f32_32x32x16_bf16 v[0:15], v[150:153], v[124:127], v[0:15]
	s_waitcnt lgkmcnt(3)
	v_mov_b32_e32 v140, v130
	v_mov_b32_e32 v141, v131
	s_waitcnt lgkmcnt(2)
	v_mov_b32_e32 v142, v134
	v_mov_b32_e32 v143, v135
	v_mov_b32_e32 v134, v132
	v_mov_b32_e32 v135, v133
	s_waitcnt lgkmcnt(1)
	v_mov_b32_e32 v130, v154
	v_mov_b32_e32 v131, v155
	s_waitcnt lgkmcnt(0)
	v_mov_b32_e32 v132, v164
	v_mov_b32_e32 v133, v165
	v_mfma_f32_32x32x16_bf16 v[48:63], v[140:143], v[120:123], v[48:63]
	v_xor_b32_e32 v142, 0x60, v129
	v_xor_b32_e32 v143, 0x70, v129
	v_add3_u32 v183, v173, v142, v160
	v_add3_u32 v184, v173, v143, v160
	v_mov_b32_e32 v164, v156
	v_mov_b32_e32 v165, v157
	v_mfma_f32_32x32x16_bf16 v[32:47], v[134:137], v[120:123], v[32:47]
	v_mfma_f32_32x32x16_bf16 v[16:31], v[130:133], v[120:123], v[16:31]
	ds_read2st64_b64 v[130:133], v183 offset1:32
	ds_read2st64_b64 v[134:137], v184 offset1:32
	ds_read2st64_b64 v[150:153], v183 offset0:64 offset1:96
	ds_read2st64_b64 v[154:157], v184 offset0:64 offset1:96
	v_mfma_f32_32x32x16_bf16 v[0:15], v[164:167], v[120:123], v[0:15]
	s_waitcnt lgkmcnt(3)
	v_mov_b32_e32 v164, v130
	v_mov_b32_e32 v165, v131
	s_waitcnt lgkmcnt(2)
; #define LAS __attribute__((address_space(3)))
; DI void attn_prompt_item(const Params& p, int item, ldsp lds, int tid_) {
;     ...
;     {
;       u32x2 va[4][2], vb[4][2];
;     ...
; #pragma unroll
;       for (int dt = 0; dt < 4; ++dt) { va[dt][0] = *(const LAS u32x2*)VF_ADDR(0, dt, 0); va[dt][1] = *(const LAS u32x2*)VF_ADDR(0, dt, 1); }
; #pragma unroll
;       for (int gi = 0; gi < 16; ++gi) {
;         if (gi + 1 < 16) {
; #pragma unroll
;           for (int dt = 0; dt < 4; ++dt) {
;             if (gi & 1) { va[dt][0] = *(const LAS u32x2*)VF_ADDR(gi + 1, dt, 0); va[dt][1] = *(const LAS u32x2*)VF_ADDR(gi + 1, dt, 1); }
;             else { vb[dt][0] = *(const LAS u32x2*)VF_ADDR(gi + 1, dt, 0); vb[dt][1] = *(const LAS u32x2*)VF_ADDR(gi + 1, dt, 1); } } }
; #pragma unroll
;         for (int dt = 0; dt < 4; ++dt) { const u32x2 lo = (gi & 1) ? vb[dt][0] : va[dt][0], hi = (gi & 1) ? vb[dt][1] : va[dt][1];
;           u32x4 vw; vw.x = lo.x; vw.y = lo.y; vw.z = hi.x; vw.w = hi.y;
;           O[dt] = __builtin_amdgcn_mfma_f32_32x32x16_bf16(__builtin_bit_cast(bf16x8, vw), pb[gi >> 1][gi & 1], O[dt], 0, 0, 0); }
;         __builtin_amdgcn_sched_barrier(0);
;       }
	v_mov_b32_e32 v166, v134
	v_mov_b32_e32 v167, v135
	v_mov_b32_e32 v134, v132
	v_mov_b32_e32 v135, v133
	s_waitcnt lgkmcnt(1)
	v_mov_b32_e32 v130, v150
	v_mov_b32_e32 v131, v151
	s_waitcnt lgkmcnt(0)
	v_mov_b32_e32 v132, v154
	v_mov_b32_e32 v133, v155
	v_xor_b32_e32 v140, 0x80, v129
	v_xor_b32_e32 v141, 0x90, v129
	v_add3_u32 v185, v173, v140, v160
	v_add3_u32 v186, v173, v141, v160
	v_mfma_f32_32x32x16_bf16 v[48:63], v[164:167], v[116:119], v[48:63]
	v_mov_b32_e32 v154, v152
	v_mov_b32_e32 v155, v153
	v_mfma_f32_32x32x16_bf16 v[32:47], v[134:137], v[116:119], v[32:47]
	v_mfma_f32_32x32x16_bf16 v[16:31], v[130:133], v[116:119], v[16:31]
	ds_read2st64_b64 v[130:133], v185 offset1:32
	ds_read2st64_b64 v[134:137], v186 offset1:32
	ds_read2st64_b64 v[150:153], v185 offset0:64 offset1:96
	ds_read2st64_b64 v[164:167], v186 offset0:64 offset1:96
	v_mfma_f32_32x32x16_bf16 v[0:15], v[154:157], v[116:119], v[0:15]
	s_waitcnt lgkmcnt(2)
	v_mov_b32_e32 v156, v134
	v_mov_b32_e32 v157, v135
	v_mov_b32_e32 v134, v132
	v_mov_b32_e32 v135, v133
	v_mov_b32_e32 v154, v130
	v_mov_b32_e32 v155, v131
	s_waitcnt lgkmcnt(1)
	v_mov_b32_e32 v130, v150
	v_mov_b32_e32 v131, v151
	s_waitcnt lgkmcnt(0)
	v_mov_b32_e32 v132, v164
	v_mov_b32_e32 v133, v165
	v_mfma_f32_32x32x16_bf16 v[32:47], v[134:137], v[112:115], v[32:47]
	v_xor_b32_e32 v137, 0xa0, v129
	v_xor_b32_e32 v138, 0xb0, v129
	v_add3_u32 v187, v173, v137, v160
	v_add3_u32 v188, v173, v138, v160
	v_mov_b32_e32 v164, v152
	v_mov_b32_e32 v165, v153
	v_mfma_f32_32x32x16_bf16 v[48:63], v[154:157], v[112:115], v[48:63]
	v_mfma_f32_32x32x16_bf16 v[16:31], v[130:133], v[112:115], v[16:31]
	ds_read2st64_b64 v[130:133], v187 offset1:32
	ds_read2st64_b64 v[150:153], v188 offset1:32
	ds_read2st64_b64 v[154:157], v187 offset0:64 offset1:96
	ds_read2st64_b64 v[174:177], v188 offset0:64 offset1:96
	v_mfma_f32_32x32x16_bf16 v[0:15], v[164:167], v[112:115], v[0:15]
	s_waitcnt lgkmcnt(3)
	v_mov_b32_e32 v164, v130
	v_mov_b32_e32 v165, v131
	s_waitcnt lgkmcnt(2)
	v_mov_b32_e32 v166, v150
	v_mov_b32_e32 v167, v151
	v_mov_b32_e32 v150, v132
	v_mov_b32_e32 v151, v133
	s_waitcnt lgkmcnt(1)
	v_mov_b32_e32 v130, v154
	v_mov_b32_e32 v131, v155
	s_waitcnt lgkmcnt(0)
	v_mov_b32_e32 v132, v174
	v_mov_b32_e32 v133, v175
	v_xor_b32_e32 v135, 0xc0, v129
	v_xor_b32_e32 v136, 0xd0, v129
	v_add3_u32 v189, v173, v135, v160
	v_add3_u32 v190, v173, v136, v160
	v_mfma_f32_32x32x16_bf16 v[48:63], v[164:167], v[104:107], v[48:63]
	v_mov_b32_e32 v174, v156
	v_mov_b32_e32 v175, v157
	v_mfma_f32_32x32x16_bf16 v[32:47], v[150:153], v[104:107], v[32:47]
	v_mfma_f32_32x32x16_bf16 v[16:31], v[130:133], v[104:107], v[16:31]
	ds_read2st64_b64 v[130:133], v189 offset1:32
	ds_read2st64_b64 v[150:153], v190 offset1:32
	ds_read2st64_b64 v[154:157], v189 offset0:64 offset1:96
	ds_read2st64_b64 v[164:167], v190 offset0:64 offset1:96
	v_mfma_f32_32x32x16_bf16 v[0:15], v[174:177], v[104:107], v[0:15]
	s_waitcnt lgkmcnt(2)
	v_mov_b32_e32 v176, v150
	v_mov_b32_e32 v177, v151
	v_mov_b32_e32 v150, v132
	v_mov_b32_e32 v151, v133
	v_mov_b32_e32 v174, v130
	v_mov_b32_e32 v175, v131
	v_mfma_f32_32x32x16_bf16 v[32:47], v[150:153], v[100:103], v[32:47]
	s_waitcnt lgkmcnt(1)
	v_mov_b32_e32 v150, v154
	v_mov_b32_e32 v151, v155
	s_waitcnt lgkmcnt(0)
	v_mov_b32_e32 v152, v164
	v_mov_b32_e32 v153, v165
	v_xor_b32_e32 v133, 0xe0, v129
	v_xor_b32_e32 v134, 0xf0, v129
	v_add3_u32 v130, v173, v133, v160
	v_add3_u32 v131, v173, v134, v160
	v_mfma_f32_32x32x16_bf16 v[48:63], v[174:177], v[100:103], v[48:63]
	v_mov_b32_e32 v164, v156
	v_mov_b32_e32 v165, v157
	v_mfma_f32_32x32x16_bf16 v[16:31], v[150:153], v[100:103], v[16:31]
	ds_read2st64_b64 v[150:153], v130 offset1:32
	ds_read2st64_b64 v[154:157], v131 offset1:32
	ds_read2st64_b64 v[174:177], v130 offset0:64 offset1:96
	ds_read2st64_b64 v[178:181], v131 offset0:64 offset1:96
	v_mfma_f32_32x32x16_bf16 v[0:15], v[164:167], v[100:103], v[0:15]
	s_waitcnt lgkmcnt(3)
	v_mov_b32_e32 v164, v150
	v_mov_b32_e32 v165, v151
	s_waitcnt lgkmcnt(2)
	v_mov_b32_e32 v166, v154
	v_mov_b32_e32 v167, v155
	v_mov_b32_e32 v154, v152
	v_mov_b32_e32 v155, v153
	s_waitcnt lgkmcnt(1)
	v_mov_b32_e32 v150, v174
	v_mov_b32_e32 v151, v175
	s_waitcnt lgkmcnt(0)
	v_mov_b32_e32 v152, v178
	v_mov_b32_e32 v153, v179
	v_add3_u32 v132, v173, v129, v160
	v_mfma_f32_32x32x16_bf16 v[48:63], v[164:167], v[96:99], v[48:63]
	v_add_u32_e32 v164, 0x100, v132
	v_xor_b32_e32 v132, 16, v129
	v_mov_b32_e32 v178, v176
	v_mov_b32_e32 v179, v177
	v_mfma_f32_32x32x16_bf16 v[16:31], v[150:153], v[96:99], v[16:31]
	v_add3_u32 v150, v173, v132, v160
	v_add_u32_e32 v173, 0x100, v150
	v_mfma_f32_32x32x16_bf16 v[32:47], v[154:157], v[96:99], v[32:47]
	ds_read2st64_b64 v[154:157], v164 offset1:32
	ds_read2st64_b64 v[150:153], v173 offset1:32
	ds_read2st64_b64 v[164:167], v164 offset0:64 offset1:96
	ds_read2st64_b64 v[174:177], v173 offset0:64 offset1:96
	v_mfma_f32_32x32x16_bf16 v[0:15], v[178:181], v[96:99], v[0:15]
	s_waitcnt lgkmcnt(2)
	v_mov_b32_e32 v180, v150
	v_mov_b32_e32 v181, v151
	v_mov_b32_e32 v150, v156
	v_mov_b32_e32 v151, v157
	v_mov_b32_e32 v178, v154
	v_mov_b32_e32 v179, v155
	v_mfma_f32_32x32x16_bf16 v[32:47], v[150:153], v[92:95], v[32:47]
	s_waitcnt lgkmcnt(1)
	v_mov_b32_e32 v150, v164
	v_mov_b32_e32 v151, v165
	s_waitcnt lgkmcnt(0)
	v_mov_b32_e32 v152, v174
	v_mov_b32_e32 v153, v175
	v_add_u32_e32 v149, 0x100, v149
	v_add_u32_e32 v158, 0x100, v158
	v_mov_b32_e32 v174, v166
	v_mfma_f32_32x32x16_bf16 v[48:63], v[178:181], v[92:95], v[48:63]
	v_mov_b32_e32 v175, v167
	v_mfma_f32_32x32x16_bf16 v[16:31], v[150:153], v[92:95], v[16:31]
	ds_read2st64_b64 v[150:153], v149 offset1:32
	ds_read2st64_b64 v[154:157], v158 offset1:32
	ds_read2st64_b64 v[164:167], v149 offset0:64 offset1:96
	ds_read2st64_b64 v[178:181], v158 offset0:64 offset1:96
	v_mfma_f32_32x32x16_bf16 v[0:15], v[174:177], v[92:95], v[0:15]
	s_waitcnt lgkmcnt(3)
; #define LAS __attribute__((address_space(3)))
; DI void attn_prompt_item(const Params& p, int item, ldsp lds, int tid_) {
;     ...
;     {
;       u32x2 va[4][2], vb[4][2];
;     ...
; #pragma unroll
;       for (int dt = 0; dt < 4; ++dt) { va[dt][0] = *(const LAS u32x2*)VF_ADDR(0, dt, 0); va[dt][1] = *(const LAS u32x2*)VF_ADDR(0, dt, 1); }
; #pragma unroll
;       for (int gi = 0; gi < 16; ++gi) {
;         if (gi + 1 < 16) {
; #pragma unroll
;           for (int dt = 0; dt < 4; ++dt) {
;             if (gi & 1) { va[dt][0] = *(const LAS u32x2*)VF_ADDR(gi + 1, dt, 0); va[dt][1] = *(const LAS u32x2*)VF_ADDR(gi + 1, dt, 1); }
;             else { vb[dt][0] = *(const LAS u32x2*)VF_ADDR(gi + 1, dt, 0); vb[dt][1] = *(const LAS u32x2*)VF_ADDR(gi + 1, dt, 1); } } }
; #pragma unroll
;         for (int dt = 0; dt < 4; ++dt) { const u32x2 lo = (gi & 1) ? vb[dt][0] : va[dt][0], hi = (gi & 1) ? vb[dt][1] : va[dt][1];
;           u32x4 vw; vw.x = lo.x; vw.y = lo.y; vw.z = hi.x; vw.w = hi.y;
;           O[dt] = __builtin_amdgcn_mfma_f32_32x32x16_bf16(__builtin_bit_cast(bf16x8, vw), pb[gi >> 1][gi & 1], O[dt], 0, 0, 0); }
;         __builtin_amdgcn_sched_barrier(0);
;       }
	v_mov_b32_e32 v174, v150
	v_mov_b32_e32 v175, v151
	s_waitcnt lgkmcnt(2)
	v_mov_b32_e32 v176, v154
	v_mov_b32_e32 v177, v155
	v_mov_b32_e32 v154, v152
	v_mov_b32_e32 v155, v153
	s_waitcnt lgkmcnt(1)
	v_mov_b32_e32 v150, v164
	v_mov_b32_e32 v151, v165
	s_waitcnt lgkmcnt(0)
	v_mov_b32_e32 v152, v178
	v_mov_b32_e32 v153, v179
	v_add_u32_e32 v149, 0x100, v159
	v_add_u32_e32 v158, 0x100, v182
	v_mfma_f32_32x32x16_bf16 v[48:63], v[174:177], v[88:91], v[48:63]
	v_mov_b32_e32 v178, v166
	v_mov_b32_e32 v179, v167
	v_mfma_f32_32x32x16_bf16 v[32:47], v[154:157], v[88:91], v[32:47]
	v_mfma_f32_32x32x16_bf16 v[16:31], v[150:153], v[88:91], v[16:31]
	ds_read2st64_b64 v[150:153], v149 offset1:32
	ds_read2st64_b64 v[154:157], v158 offset1:32
	ds_read2st64_b64 v[164:167], v149 offset0:64 offset1:96
	ds_read2st64_b64 v[174:177], v158 offset0:64 offset1:96
	v_mfma_f32_32x32x16_bf16 v[0:15], v[178:181], v[88:91], v[0:15]
	s_waitcnt lgkmcnt(3)
	v_mov_b32_e32 v178, v150
	v_mov_b32_e32 v179, v151
	s_waitcnt lgkmcnt(2)
	v_mov_b32_e32 v180, v154
	v_mov_b32_e32 v181, v155
	v_mov_b32_e32 v154, v152
	v_mov_b32_e32 v155, v153
	s_waitcnt lgkmcnt(1)
	v_mov_b32_e32 v150, v164
	v_mov_b32_e32 v151, v165
	s_waitcnt lgkmcnt(0)
	v_mov_b32_e32 v152, v174
	v_mov_b32_e32 v153, v175
	v_add_u32_e32 v149, 0x100, v183
	v_add_u32_e32 v158, 0x100, v184
	v_mfma_f32_32x32x16_bf16 v[48:63], v[178:181], v[84:87], v[48:63]
	v_mov_b32_e32 v174, v166
	v_mov_b32_e32 v175, v167
	v_mfma_f32_32x32x16_bf16 v[32:47], v[154:157], v[84:87], v[32:47]
	v_mfma_f32_32x32x16_bf16 v[16:31], v[150:153], v[84:87], v[16:31]
	ds_read2st64_b64 v[150:153], v149 offset1:32
	ds_read2st64_b64 v[154:157], v158 offset1:32
	ds_read2st64_b64 v[164:167], v149 offset0:64 offset1:96
	ds_read2st64_b64 v[178:181], v158 offset0:64 offset1:96
	v_mfma_f32_32x32x16_bf16 v[0:15], v[174:177], v[84:87], v[0:15]
	s_waitcnt lgkmcnt(3)
	v_mov_b32_e32 v174, v150
	v_mov_b32_e32 v175, v151
	s_waitcnt lgkmcnt(2)
	v_mov_b32_e32 v176, v154
	v_mov_b32_e32 v177, v155
	v_mov_b32_e32 v154, v152
	v_mov_b32_e32 v155, v153
	s_waitcnt lgkmcnt(1)
	v_mov_b32_e32 v150, v164
	v_mov_b32_e32 v151, v165
	s_waitcnt lgkmcnt(0)
	v_mov_b32_e32 v152, v178
	v_mov_b32_e32 v153, v179
	v_add_u32_e32 v149, 0x100, v185
	v_add_u32_e32 v158, 0x100, v186
	v_mfma_f32_32x32x16_bf16 v[48:63], v[174:177], v[80:83], v[48:63]
	v_mov_b32_e32 v178, v166
	v_mov_b32_e32 v179, v167
	v_mfma_f32_32x32x16_bf16 v[32:47], v[154:157], v[80:83], v[32:47]
	v_mfma_f32_32x32x16_bf16 v[16:31], v[150:153], v[80:83], v[16:31]
	ds_read2st64_b64 v[150:153], v149 offset1:32
	ds_read2st64_b64 v[154:157], v158 offset1:32
	ds_read2st64_b64 v[164:167], v149 offset0:64 offset1:96
	ds_read2st64_b64 v[174:177], v158 offset0:64 offset1:96
	v_mfma_f32_32x32x16_bf16 v[0:15], v[178:181], v[80:83], v[0:15]
	s_waitcnt lgkmcnt(3)
	v_mov_b32_e32 v178, v150
	v_mov_b32_e32 v179, v151
	s_waitcnt lgkmcnt(2)
	v_mov_b32_e32 v180, v154
	v_mov_b32_e32 v181, v155
	v_mov_b32_e32 v154, v152
	v_mov_b32_e32 v155, v153
	s_waitcnt lgkmcnt(1)
	v_mov_b32_e32 v150, v164
	v_mov_b32_e32 v151, v165
	s_waitcnt lgkmcnt(0)
	v_mov_b32_e32 v152, v174
	v_mov_b32_e32 v153, v175
	v_add_u32_e32 v149, 0x100, v187
	v_add_u32_e32 v158, 0x100, v188
	v_mfma_f32_32x32x16_bf16 v[48:63], v[178:181], v[76:79], v[48:63]
	v_mov_b32_e32 v174, v166
	v_mov_b32_e32 v175, v167
	v_mfma_f32_32x32x16_bf16 v[32:47], v[154:157], v[76:79], v[32:47]
	v_mfma_f32_32x32x16_bf16 v[16:31], v[150:153], v[76:79], v[16:31]
	ds_read2st64_b64 v[150:153], v149 offset1:32
	ds_read2st64_b64 v[154:157], v158 offset1:32
	ds_read2st64_b64 v[164:167], v149 offset0:64 offset1:96
	ds_read2st64_b64 v[178:181], v158 offset0:64 offset1:96
	v_mfma_f32_32x32x16_bf16 v[0:15], v[174:177], v[76:79], v[0:15]
	s_waitcnt lgkmcnt(3)
	v_mov_b32_e32 v174, v150
	v_mov_b32_e32 v175, v151
	s_waitcnt lgkmcnt(2)
	v_mov_b32_e32 v176, v154
	v_mov_b32_e32 v177, v155
	v_mov_b32_e32 v154, v152
	v_mov_b32_e32 v155, v153
	s_waitcnt lgkmcnt(1)
	v_mov_b32_e32 v150, v164
	v_mov_b32_e32 v151, v165
	s_waitcnt lgkmcnt(0)
	v_mov_b32_e32 v152, v178
	v_mov_b32_e32 v153, v179
	v_add_u32_e32 v149, 0x100, v189
	v_add_u32_e32 v158, 0x100, v190
	v_mfma_f32_32x32x16_bf16 v[48:63], v[174:177], v[72:75], v[48:63]
	v_mov_b32_e32 v178, v166
	v_mov_b32_e32 v179, v167
	v_mfma_f32_32x32x16_bf16 v[32:47], v[154:157], v[72:75], v[32:47]
	v_mfma_f32_32x32x16_bf16 v[16:31], v[150:153], v[72:75], v[16:31]
	ds_read2st64_b64 v[150:153], v149 offset1:32
	ds_read2st64_b64 v[154:157], v158 offset1:32
	ds_read2st64_b64 v[164:167], v149 offset0:64 offset1:96
	ds_read2st64_b64 v[174:177], v158 offset0:64 offset1:96
	v_mfma_f32_32x32x16_bf16 v[0:15], v[178:181], v[72:75], v[0:15]
	s_waitcnt lgkmcnt(3)
	v_mov_b32_e32 v178, v150
	v_mov_b32_e32 v179, v151
	s_waitcnt lgkmcnt(2)
	v_mov_b32_e32 v180, v154
	v_mov_b32_e32 v181, v155
	v_mov_b32_e32 v154, v152
	v_mov_b32_e32 v155, v153
	s_waitcnt lgkmcnt(1)
	v_mov_b32_e32 v150, v164
	v_mov_b32_e32 v151, v165
	s_waitcnt lgkmcnt(0)
	v_mov_b32_e32 v152, v174
	v_mov_b32_e32 v153, v175
	v_add_u32_e32 v130, 0x100, v130
	v_add_u32_e32 v131, 0x100, v131
	v_mfma_f32_32x32x16_bf16 v[48:63], v[178:181], v[68:71], v[48:63]
	v_mov_b32_e32 v174, v166
	v_mov_b32_e32 v175, v167
	v_mfma_f32_32x32x16_bf16 v[32:47], v[154:157], v[68:71], v[32:47]
	v_mfma_f32_32x32x16_bf16 v[16:31], v[150:153], v[68:71], v[16:31]
	ds_read2st64_b64 v[150:153], v130 offset1:32
	ds_read2st64_b64 v[154:157], v131 offset1:32
	ds_read2st64_b64 v[164:167], v130 offset0:64 offset1:96
	ds_read2st64_b64 v[178:181], v131 offset0:64 offset1:96
	v_mfma_f32_32x32x16_bf16 v[0:15], v[174:177], v[68:71], v[0:15]
	s_waitcnt lgkmcnt(3)
; #define LAS __attribute__((address_space(3)))
; DI unsigned pk2(float lo, float hi) { f32x2 v = {lo, hi}; return __builtin_bit_cast(unsigned, __builtin_convertvector(v, bf16x2v)); }
; DI void attn_prompt_item(const Params& p, int item, ldsp lds, int tid_) {
;     ...
;   for (int dh = 0; dh < 2; ++dh) {
;     f32x16 O[4];
; #pragma unroll
;     for (int dt = 0; dt < 4; ++dt)
; #pragma unroll
;       for (int i = 0; i < 16; ++i) O[dt][i] = 0.f;
;     {
;       u32x2 va[4][2], vb[4][2];
;     ...
; #pragma unroll
;       for (int dt = 0; dt < 4; ++dt) { va[dt][0] = *(const LAS u32x2*)VF_ADDR(0, dt, 0); va[dt][1] = *(const LAS u32x2*)VF_ADDR(0, dt, 1); }
; #pragma unroll
;       for (int gi = 0; gi < 16; ++gi) {
;         if (gi + 1 < 16) {
; #pragma unroll
;           for (int dt = 0; dt < 4; ++dt) {
;             if (gi & 1) { va[dt][0] = *(const LAS u32x2*)VF_ADDR(gi + 1, dt, 0); va[dt][1] = *(const LAS u32x2*)VF_ADDR(gi + 1, dt, 1); }
;             else { vb[dt][0] = *(const LAS u32x2*)VF_ADDR(gi + 1, dt, 0); vb[dt][1] = *(const LAS u32x2*)VF_ADDR(gi + 1, dt, 1); } } }
; #pragma unroll
;         for (int dt = 0; dt < 4; ++dt) { const u32x2 lo = (gi & 1) ? vb[dt][0] : va[dt][0], hi = (gi & 1) ? vb[dt][1] : va[dt][1];
;           u32x4 vw; vw.x = lo.x; vw.y = lo.y; vw.z = hi.x; vw.w = hi.y;
;           O[dt] = __builtin_amdgcn_mfma_f32_32x32x16_bf16(__builtin_bit_cast(bf16x8, vw), pb[gi >> 1][gi & 1], O[dt], 0, 0, 0); }
;         __builtin_amdgcn_sched_barrier(0);
;       }
;     ...
;     }
; #pragma unroll
;     for (int dt = 0; dt < 4; ++dt)
; #pragma unroll
;       for (int g4 = 0; g4 < 4; ++g4) { u32x2 w; w.x = pk2(O[dt][4 * g4] * inv, O[dt][4 * g4 + 1] * inv); w.y = pk2(O[dt][4 * g4 + 2] * inv, O[dt][4 * g4 + 3] * inv);
;         *(u32x2*)((bf16_t*)(p.ws + B_XA) + qrow * D + h * 256 + (dh * 4 + dt) * 32 + 8 * g4 + 4 * h2) = w; }
	v_mov_b32_e32 v174, v150
	v_mov_b32_e32 v175, v151
	s_waitcnt lgkmcnt(2)
	v_mov_b32_e32 v176, v154
	v_mov_b32_e32 v177, v155
	v_mov_b32_e32 v154, v152
	v_mov_b32_e32 v155, v153
	s_waitcnt lgkmcnt(1)
	v_mov_b32_e32 v150, v164
	v_mov_b32_e32 v151, v165
	s_waitcnt lgkmcnt(0)
	v_mov_b32_e32 v152, v178
	v_mov_b32_e32 v153, v179
	v_mov_b32_e32 v178, v166
	v_mov_b32_e32 v179, v167
	v_mfma_f32_32x32x16_bf16 v[48:63], v[174:177], v[64:67], v[48:63]
	v_mfma_f32_32x32x16_bf16 v[32:47], v[154:157], v[64:67], v[32:47]
	v_mfma_f32_32x32x16_bf16 v[16:31], v[150:153], v[64:67], v[16:31]
	v_mfma_f32_32x32x16_bf16 v[0:15], v[178:181], v[64:67], v[0:15]
	s_nop 8
	v_lshl_add_u64 v[196:197], s[42:43], 0, v[162:163]
	v_lshl_add_u64 v[196:197], v[196:197], 0, s[26:27]
	v_lshl_add_u64 v[196:197], v[196:197], 0, v[160:161]
	v_add_co_u32_e32 v130, vcc, s38, v196
	v_mbcnt_lo_u32_b32 v198, -1, 0
	v_mbcnt_hi_u32_b32 v198, -1, v198
	v_addc_co_u32_e32 v131, vcc, 0, v197, vcc
	v_and_b32_e32 v198, 32, v198
	v_lshrrev_b32_e32 v198, 2, v198
	v_mov_b32_e32 v199, 0
	v_lshl_add_u64 v[130:131], v[130:131], 0, v[198:199]
	v_pk_mul_f32 v[48:49], v[128:129], v[48:49] op_sel_hi:[0,1]
	v_pk_mul_f32 v[50:51], v[128:129], v[50:51] op_sel_hi:[0,1]
	v_pk_mul_f32 v[52:53], v[128:129], v[52:53] op_sel_hi:[0,1]
	v_pk_mul_f32 v[54:55], v[128:129], v[54:55] op_sel_hi:[0,1]
	v_cvt_pk_bf16_f32 v48, v48, v49
	v_cvt_pk_bf16_f32 v49, v50, v51
	v_cvt_pk_bf16_f32 v50, v52, v53
	v_cvt_pk_bf16_f32 v51, v54, v55
	v_pk_mul_f32 v[32:33], v[128:129], v[32:33] op_sel_hi:[0,1]
	v_pk_mul_f32 v[34:35], v[128:129], v[34:35] op_sel_hi:[0,1]
	v_pk_mul_f32 v[36:37], v[128:129], v[36:37] op_sel_hi:[0,1]
	v_pk_mul_f32 v[38:39], v[128:129], v[38:39] op_sel_hi:[0,1]
	v_cvt_pk_bf16_f32 v32, v32, v33
	v_cvt_pk_bf16_f32 v33, v34, v35
	v_cvt_pk_bf16_f32 v34, v36, v37
	v_cvt_pk_bf16_f32 v35, v38, v39
	v_pk_mul_f32 v[16:17], v[128:129], v[16:17] op_sel_hi:[0,1]
	v_pk_mul_f32 v[18:19], v[128:129], v[18:19] op_sel_hi:[0,1]
	v_pk_mul_f32 v[20:21], v[128:129], v[20:21] op_sel_hi:[0,1]
	v_pk_mul_f32 v[22:23], v[128:129], v[22:23] op_sel_hi:[0,1]
	v_cvt_pk_bf16_f32 v16, v16, v17
	v_cvt_pk_bf16_f32 v17, v18, v19
	v_cvt_pk_bf16_f32 v18, v20, v21
	v_cvt_pk_bf16_f32 v19, v22, v23
	v_pk_mul_f32 v[0:1], v[128:129], v[0:1] op_sel_hi:[0,1]
	v_pk_mul_f32 v[2:3], v[128:129], v[2:3] op_sel_hi:[0,1]
	v_pk_mul_f32 v[4:5], v[128:129], v[4:5] op_sel_hi:[0,1]
	v_pk_mul_f32 v[6:7], v[128:129], v[6:7] op_sel_hi:[0,1]
	v_cvt_pk_bf16_f32 v0, v0, v1
	v_cvt_pk_bf16_f32 v1, v2, v3
	v_cvt_pk_bf16_f32 v2, v4, v5
	v_cvt_pk_bf16_f32 v3, v6, v7
	s_nop 1
	v_permlane32_swap_b32_e32 v48, v50
	v_permlane32_swap_b32_e32 v49, v51
	global_store_dwordx4 v[130:131], v[48:51], off
	v_permlane32_swap_b32_e32 v32, v34
	v_permlane32_swap_b32_e32 v33, v35
	global_store_dwordx4 v[130:131], v[32:35], off offset:64
	v_permlane32_swap_b32_e32 v16, v18
	v_permlane32_swap_b32_e32 v17, v19
	global_store_dwordx4 v[130:131], v[16:19], off offset:128
	v_permlane32_swap_b32_e32 v0, v2
	v_permlane32_swap_b32_e32 v1, v3
	global_store_dwordx4 v[130:131], v[0:3], off offset:192
	v_pk_mul_f32 v[56:57], v[128:129], v[56:57] op_sel_hi:[0,1]
	v_pk_mul_f32 v[58:59], v[128:129], v[58:59] op_sel_hi:[0,1]
	v_pk_mul_f32 v[60:61], v[128:129], v[60:61] op_sel_hi:[0,1]
	v_pk_mul_f32 v[62:63], v[128:129], v[62:63] op_sel_hi:[0,1]
	v_cvt_pk_bf16_f32 v56, v56, v57
	v_cvt_pk_bf16_f32 v57, v58, v59
	v_cvt_pk_bf16_f32 v58, v60, v61
	v_cvt_pk_bf16_f32 v59, v62, v63
	v_pk_mul_f32 v[40:41], v[128:129], v[40:41] op_sel_hi:[0,1]
	v_pk_mul_f32 v[42:43], v[128:129], v[42:43] op_sel_hi:[0,1]
	v_pk_mul_f32 v[44:45], v[128:129], v[44:45] op_sel_hi:[0,1]
	v_pk_mul_f32 v[46:47], v[128:129], v[46:47] op_sel_hi:[0,1]
	v_cvt_pk_bf16_f32 v40, v40, v41
	v_cvt_pk_bf16_f32 v41, v42, v43
	v_cvt_pk_bf16_f32 v42, v44, v45
	v_cvt_pk_bf16_f32 v43, v46, v47
	v_pk_mul_f32 v[24:25], v[128:129], v[24:25] op_sel_hi:[0,1]
	v_pk_mul_f32 v[26:27], v[128:129], v[26:27] op_sel_hi:[0,1]
	v_pk_mul_f32 v[28:29], v[128:129], v[28:29] op_sel_hi:[0,1]
	v_pk_mul_f32 v[30:31], v[128:129], v[30:31] op_sel_hi:[0,1]
	v_cvt_pk_bf16_f32 v24, v24, v25
	v_cvt_pk_bf16_f32 v25, v26, v27
	v_cvt_pk_bf16_f32 v26, v28, v29
	v_cvt_pk_bf16_f32 v27, v30, v31
	v_pk_mul_f32 v[8:9], v[128:129], v[8:9] op_sel_hi:[0,1]
	v_pk_mul_f32 v[10:11], v[128:129], v[10:11] op_sel_hi:[0,1]
	v_pk_mul_f32 v[12:13], v[128:129], v[12:13] op_sel_hi:[0,1]
	v_pk_mul_f32 v[14:15], v[128:129], v[14:15] op_sel_hi:[0,1]
	v_cvt_pk_bf16_f32 v8, v8, v9
	v_cvt_pk_bf16_f32 v9, v10, v11
	v_cvt_pk_bf16_f32 v10, v12, v13
	v_cvt_pk_bf16_f32 v11, v14, v15
	s_nop 1
	v_permlane32_swap_b32_e32 v56, v58
	v_permlane32_swap_b32_e32 v57, v59
	global_store_dwordx4 v[130:131], v[56:59], off offset:32
	v_permlane32_swap_b32_e32 v40, v42
	v_permlane32_swap_b32_e32 v41, v43
	global_store_dwordx4 v[130:131], v[40:43], off offset:96
	v_permlane32_swap_b32_e32 v24, v26
	v_permlane32_swap_b32_e32 v25, v27
	global_store_dwordx4 v[130:131], v[24:27], off offset:160
	v_permlane32_swap_b32_e32 v8, v10
	v_permlane32_swap_b32_e32 v9, v11
	global_store_dwordx4 v[130:131], v[8:11], off offset:224
	v_add_u32_e32 v158, s39, v172
	v_add3_u32 v0, v158, v146, v160
	v_add3_u32 v2, v158, v139, v160
	ds_read_b64 v[0:1], v0
	ds_read_b64 v[2:3], v2
	v_add_u32_e32 v159, s40, v172
	v_add_u32_e32 v166, s41, v172
	v_add_u32_e32 v167, s44, v172
	v_add3_u32 v4, v159, v146, v160
	v_add3_u32 v6, v159, v139, v160
	v_add3_u32 v8, v166, v146, v160
	v_add3_u32 v9, v166, v139, v160
	v_add3_u32 v10, v167, v146, v160
	v_add3_u32 v11, v167, v139, v160
	v_add3_u32 v139, v158, v147, v160
	v_add3_u32 v175, v166, v147, v160
	ds_read_b64 v[4:5], v4
	ds_read_b64 v[6:7], v6
	s_waitcnt lgkmcnt(2)
; #define LAS __attribute__((address_space(3)))
; DI void attn_prompt_item(const Params& p, int item, ldsp lds, int tid_) {
;     ...
;     {
;       u32x2 va[4][2], vb[4][2];
;     ...
; #pragma unroll
;       for (int dt = 0; dt < 4; ++dt) { va[dt][0] = *(const LAS u32x2*)VF_ADDR(0, dt, 0); va[dt][1] = *(const LAS u32x2*)VF_ADDR(0, dt, 1); }
; #pragma unroll
;       for (int gi = 0; gi < 16; ++gi) {
;         if (gi + 1 < 16) {
; #pragma unroll
;           for (int dt = 0; dt < 4; ++dt) {
;             if (gi & 1) { va[dt][0] = *(const LAS u32x2*)VF_ADDR(gi + 1, dt, 0); va[dt][1] = *(const LAS u32x2*)VF_ADDR(gi + 1, dt, 1); }
;             else { vb[dt][0] = *(const LAS u32x2*)VF_ADDR(gi + 1, dt, 0); vb[dt][1] = *(const LAS u32x2*)VF_ADDR(gi + 1, dt, 1); } } }
; #pragma unroll
;         for (int dt = 0; dt < 4; ++dt) { const u32x2 lo = (gi & 1) ? vb[dt][0] : va[dt][0], hi = (gi & 1) ? vb[dt][1] : va[dt][1];
;           u32x4 vw; vw.x = lo.x; vw.y = lo.y; vw.z = hi.x; vw.w = hi.y;
;           O[dt] = __builtin_amdgcn_mfma_f32_32x32x16_bf16(__builtin_bit_cast(bf16x8, vw), pb[gi >> 1][gi & 1], O[dt], 0, 0, 0); }
;         __builtin_amdgcn_sched_barrier(0);
;       }
	v_mfma_f32_32x32x16_bf16 v[48:63], v[0:3], v[108:111], 0
	ds_read_b64 v[0:1], v8
	ds_read_b64 v[2:3], v9
	ds_read_b64 v[8:9], v10
	ds_read_b64 v[10:11], v11
	v_add3_u32 v172, v158, v148, v160
	v_add3_u32 v173, v159, v147, v160
	v_add3_u32 v174, v159, v148, v160
	ds_read_b64 v[150:151], v139
	ds_read_b64 v[152:153], v172
	ds_read_b64 v[154:155], v173
	ds_read_b64 v[156:157], v174
	v_add3_u32 v176, v166, v148, v160
	v_add3_u32 v177, v167, v147, v160
	v_add3_u32 v178, v167, v148, v160
	ds_read_b64 v[146:147], v175
	ds_read_b64 v[148:149], v176
	ds_read_b64 v[162:163], v177
	ds_read_b64 v[164:165], v178
	s_waitcnt lgkmcnt(12)
	v_mfma_f32_32x32x16_bf16 v[32:47], v[4:7], v[108:111], 0
	s_waitcnt lgkmcnt(10)
	v_mfma_f32_32x32x16_bf16 v[16:31], v[0:3], v[108:111], 0
	s_waitcnt lgkmcnt(8)
	v_mfma_f32_32x32x16_bf16 v[0:15], v[8:11], v[108:111], 0
	v_add3_u32 v179, v158, v144, v160
	v_add3_u32 v183, v166, v144, v160
	s_waitcnt lgkmcnt(6)
	v_mfma_f32_32x32x16_bf16 v[48:63], v[150:153], v[124:127], v[48:63]
	v_add3_u32 v180, v158, v145, v160
	v_add3_u32 v181, v159, v144, v160
	v_add3_u32 v182, v159, v145, v160
	ds_read_b64 v[108:109], v179
	ds_read_b64 v[110:111], v180
	ds_read_b64 v[150:151], v181
	ds_read_b64 v[152:153], v182
	v_add3_u32 v184, v166, v145, v160
	v_add3_u32 v185, v167, v144, v160
	v_add3_u32 v186, v167, v145, v160
	s_waitcnt lgkmcnt(8)
	v_mfma_f32_32x32x16_bf16 v[32:47], v[154:157], v[124:127], v[32:47]
	s_waitcnt lgkmcnt(6)
	v_mfma_f32_32x32x16_bf16 v[16:31], v[146:149], v[124:127], v[16:31]
	ds_read_b64 v[144:145], v183
	ds_read_b64 v[146:147], v184
	ds_read_b64 v[154:155], v185
	ds_read_b64 v[156:157], v186
	s_waitcnt lgkmcnt(8)
	v_mfma_f32_32x32x16_bf16 v[0:15], v[162:165], v[124:127], v[0:15]
	v_add3_u32 v162, v158, v142, v160
	s_waitcnt lgkmcnt(4)
	v_mfma_f32_32x32x16_bf16 v[32:47], v[150:153], v[120:123], v[32:47]
	v_add3_u32 v152, v166, v142, v160
	v_add3_u32 v163, v158, v143, v160
	v_add3_u32 v150, v159, v142, v160
	v_add3_u32 v151, v159, v143, v160
	v_add3_u32 v153, v166, v143, v160
	v_add3_u32 v164, v167, v142, v160
	v_add3_u32 v165, v167, v143, v160
	v_mfma_f32_32x32x16_bf16 v[48:63], v[108:111], v[120:123], v[48:63]
	ds_read_b64 v[108:109], v162
	ds_read_b64 v[110:111], v163
	ds_read_b64 v[124:125], v150
	ds_read_b64 v[126:127], v151
	s_waitcnt lgkmcnt(6)
	v_mfma_f32_32x32x16_bf16 v[16:31], v[144:147], v[120:123], v[16:31]
	ds_read_b64 v[142:143], v152
	ds_read_b64 v[144:145], v153
	ds_read_b64 v[146:147], v164
	ds_read_b64 v[148:149], v165
	s_waitcnt lgkmcnt(8)
	v_mfma_f32_32x32x16_bf16 v[0:15], v[154:157], v[120:123], v[0:15]
	v_add3_u32 v154, v158, v140, v160
	v_add3_u32 v187, v166, v140, v160
	s_waitcnt lgkmcnt(6)
	v_mfma_f32_32x32x16_bf16 v[48:63], v[108:111], v[116:119], v[48:63]
	v_add3_u32 v155, v158, v141, v160
	v_add3_u32 v156, v159, v140, v160
	v_add3_u32 v157, v159, v141, v160
	ds_read_b64 v[108:109], v154
	ds_read_b64 v[110:111], v155
	ds_read_b64 v[120:121], v156
	ds_read_b64 v[122:123], v157
	v_add3_u32 v188, v167, v141, v160
	s_waitcnt lgkmcnt(8)
	v_mfma_f32_32x32x16_bf16 v[32:47], v[124:127], v[116:119], v[32:47]
	s_waitcnt lgkmcnt(6)
	v_mfma_f32_32x32x16_bf16 v[16:31], v[142:145], v[116:119], v[16:31]
	v_add3_u32 v144, v166, v141, v160
	v_add3_u32 v145, v167, v140, v160
	ds_read_b64 v[124:125], v187
	ds_read_b64 v[126:127], v144
	ds_read_b64 v[140:141], v145
	ds_read_b64 v[142:143], v188
	s_waitcnt lgkmcnt(8)
	v_mfma_f32_32x32x16_bf16 v[0:15], v[146:149], v[116:119], v[0:15]
	v_add3_u32 v146, v158, v137, v160
	v_add3_u32 v189, v166, v137, v160
	s_waitcnt lgkmcnt(6)
	v_mfma_f32_32x32x16_bf16 v[48:63], v[108:111], v[112:115], v[48:63]
	v_add3_u32 v147, v158, v138, v160
	v_add3_u32 v148, v159, v137, v160
	v_add3_u32 v149, v159, v138, v160
	ds_read_b64 v[108:109], v146
	ds_read_b64 v[110:111], v147
	ds_read_b64 v[116:117], v148
	ds_read_b64 v[118:119], v149
	v_add3_u32 v190, v166, v138, v160
	v_add3_u32 v137, v167, v137, v160
	v_add3_u32 v138, v167, v138, v160
	s_waitcnt lgkmcnt(8)
	v_mfma_f32_32x32x16_bf16 v[32:47], v[120:123], v[112:115], v[32:47]
	s_waitcnt lgkmcnt(6)
	v_mfma_f32_32x32x16_bf16 v[16:31], v[124:127], v[112:115], v[16:31]
	ds_read_b64 v[120:121], v189
	ds_read_b64 v[122:123], v190
	ds_read_b64 v[124:125], v137
	ds_read_b64 v[126:127], v138
	s_waitcnt lgkmcnt(8)
	v_mfma_f32_32x32x16_bf16 v[0:15], v[140:143], v[112:115], v[0:15]
	v_add3_u32 v140, v158, v135, v160
	v_add3_u32 v191, v166, v135, v160
	s_waitcnt lgkmcnt(6)
	v_mfma_f32_32x32x16_bf16 v[48:63], v[108:111], v[104:107], v[48:63]
	v_add3_u32 v141, v158, v136, v160
	v_add3_u32 v142, v159, v135, v160
	v_add3_u32 v143, v159, v136, v160
	ds_read_b64 v[108:109], v140
	ds_read_b64 v[110:111], v141
	ds_read_b64 v[112:113], v142
	ds_read_b64 v[114:115], v143
	v_add3_u32 v192, v166, v136, v160
	v_add3_u32 v135, v167, v135, v160
	v_add3_u32 v136, v167, v136, v160
	s_waitcnt lgkmcnt(8)
	v_mfma_f32_32x32x16_bf16 v[32:47], v[116:119], v[104:107], v[32:47]
	s_waitcnt lgkmcnt(6)
	v_mfma_f32_32x32x16_bf16 v[16:31], v[120:123], v[104:107], v[16:31]
	ds_read_b64 v[116:117], v191
	ds_read_b64 v[118:119], v192
	ds_read_b64 v[120:121], v135
	ds_read_b64 v[122:123], v136
	s_waitcnt lgkmcnt(8)
	v_mfma_f32_32x32x16_bf16 v[0:15], v[124:127], v[104:107], v[0:15]
	v_add3_u32 v124, v158, v133, v160
	v_add3_u32 v193, v166, v133, v160
	s_waitcnt lgkmcnt(6)
	v_mfma_f32_32x32x16_bf16 v[48:63], v[108:111], v[100:103], v[48:63]
	v_add3_u32 v125, v158, v134, v160
	v_add3_u32 v126, v159, v133, v160
	v_add3_u32 v127, v159, v134, v160
	ds_read_b64 v[104:105], v124
	ds_read_b64 v[106:107], v125
	ds_read_b64 v[108:109], v126
	ds_read_b64 v[110:111], v127
	v_add3_u32 v194, v166, v134, v160
	v_add3_u32 v133, v167, v133, v160
	v_add3_u32 v134, v167, v134, v160
	s_waitcnt lgkmcnt(8)
; #define LAS __attribute__((address_space(3)))
; DI void attn_prompt_item(const Params& p, int item, ldsp lds, int tid_) {
;     ...
;     {
;       u32x2 va[4][2], vb[4][2];
;     ...
; #pragma unroll
;       for (int dt = 0; dt < 4; ++dt) { va[dt][0] = *(const LAS u32x2*)VF_ADDR(0, dt, 0); va[dt][1] = *(const LAS u32x2*)VF_ADDR(0, dt, 1); }
; #pragma unroll
;       for (int gi = 0; gi < 16; ++gi) {
;         if (gi + 1 < 16) {
; #pragma unroll
;           for (int dt = 0; dt < 4; ++dt) {
;             if (gi & 1) { va[dt][0] = *(const LAS u32x2*)VF_ADDR(gi + 1, dt, 0); va[dt][1] = *(const LAS u32x2*)VF_ADDR(gi + 1, dt, 1); }
;             else { vb[dt][0] = *(const LAS u32x2*)VF_ADDR(gi + 1, dt, 0); vb[dt][1] = *(const LAS u32x2*)VF_ADDR(gi + 1, dt, 1); } } }
; #pragma unroll
;         for (int dt = 0; dt < 4; ++dt) { const u32x2 lo = (gi & 1) ? vb[dt][0] : va[dt][0], hi = (gi & 1) ? vb[dt][1] : va[dt][1];
;           u32x4 vw; vw.x = lo.x; vw.y = lo.y; vw.z = hi.x; vw.w = hi.y;
;           O[dt] = __builtin_amdgcn_mfma_f32_32x32x16_bf16(__builtin_bit_cast(bf16x8, vw), pb[gi >> 1][gi & 1], O[dt], 0, 0, 0); }
;         __builtin_amdgcn_sched_barrier(0);
;       }
	v_mfma_f32_32x32x16_bf16 v[32:47], v[112:115], v[100:103], v[32:47]
	s_waitcnt lgkmcnt(6)
	v_mfma_f32_32x32x16_bf16 v[16:31], v[116:119], v[100:103], v[16:31]
	ds_read_b64 v[112:113], v193
	ds_read_b64 v[114:115], v194
	ds_read_b64 v[116:117], v133
	ds_read_b64 v[118:119], v134
	s_waitcnt lgkmcnt(8)
	v_mfma_f32_32x32x16_bf16 v[0:15], v[120:123], v[100:103], v[0:15]
	s_waitcnt lgkmcnt(6)
	v_mfma_f32_32x32x16_bf16 v[48:63], v[104:107], v[96:99], v[48:63]
	v_add3_u32 v100, v158, v129, v160
	v_add3_u32 v102, v158, v132, v160
	v_add3_u32 v104, v159, v129, v160
	v_add3_u32 v106, v159, v132, v160
	ds_read_b64 v[100:101], v100 offset:256
	ds_read_b64 v[102:103], v102 offset:256
	ds_read_b64 v[104:105], v104 offset:256
	ds_read_b64 v[106:107], v106 offset:256
	s_waitcnt lgkmcnt(8)
	v_mfma_f32_32x32x16_bf16 v[32:47], v[108:111], v[96:99], v[32:47]
	v_add3_u32 v108, v166, v129, v160
	v_add3_u32 v110, v166, v132, v160
	s_waitcnt lgkmcnt(6)
	v_mfma_f32_32x32x16_bf16 v[16:31], v[112:115], v[96:99], v[16:31]
	v_add3_u32 v112, v167, v129, v160
	v_add3_u32 v114, v167, v132, v160
	ds_read_b64 v[108:109], v108 offset:256
	ds_read_b64 v[110:111], v110 offset:256
	ds_read_b64 v[112:113], v112 offset:256
	ds_read_b64 v[114:115], v114 offset:256
	s_waitcnt lgkmcnt(8)
	v_mfma_f32_32x32x16_bf16 v[0:15], v[116:119], v[96:99], v[0:15]
	s_waitcnt lgkmcnt(6)
	v_mfma_f32_32x32x16_bf16 v[48:63], v[100:103], v[92:95], v[48:63]
	s_waitcnt lgkmcnt(4)
	v_mfma_f32_32x32x16_bf16 v[32:47], v[104:107], v[92:95], v[32:47]
	s_waitcnt lgkmcnt(2)
	v_mfma_f32_32x32x16_bf16 v[16:31], v[108:111], v[92:95], v[16:31]
	ds_read_b64 v[96:97], v139 offset:256
	ds_read_b64 v[98:99], v172 offset:256
	ds_read_b64 v[100:101], v173 offset:256
	ds_read_b64 v[102:103], v174 offset:256
	ds_read_b64 v[104:105], v175 offset:256
	ds_read_b64 v[106:107], v176 offset:256
	ds_read_b64 v[108:109], v177 offset:256
	ds_read_b64 v[110:111], v178 offset:256
	s_waitcnt lgkmcnt(8)
	v_mfma_f32_32x32x16_bf16 v[0:15], v[112:115], v[92:95], v[0:15]
	s_waitcnt lgkmcnt(6)
	v_mfma_f32_32x32x16_bf16 v[48:63], v[96:99], v[88:91], v[48:63]
	s_waitcnt lgkmcnt(4)
	v_mfma_f32_32x32x16_bf16 v[32:47], v[100:103], v[88:91], v[32:47]
	s_waitcnt lgkmcnt(2)
	v_mfma_f32_32x32x16_bf16 v[16:31], v[104:107], v[88:91], v[16:31]
	ds_read_b64 v[92:93], v179 offset:256
	ds_read_b64 v[94:95], v180 offset:256
	ds_read_b64 v[96:97], v181 offset:256
	ds_read_b64 v[98:99], v182 offset:256
	ds_read_b64 v[100:101], v183 offset:256
	ds_read_b64 v[102:103], v184 offset:256
	ds_read_b64 v[104:105], v185 offset:256
	ds_read_b64 v[106:107], v186 offset:256
	s_waitcnt lgkmcnt(8)
	v_mfma_f32_32x32x16_bf16 v[0:15], v[108:111], v[88:91], v[0:15]
	s_waitcnt lgkmcnt(6)
	v_mfma_f32_32x32x16_bf16 v[48:63], v[92:95], v[84:87], v[48:63]
	s_waitcnt lgkmcnt(4)
	v_mfma_f32_32x32x16_bf16 v[32:47], v[96:99], v[84:87], v[32:47]
	s_waitcnt lgkmcnt(2)
	v_mfma_f32_32x32x16_bf16 v[16:31], v[100:103], v[84:87], v[16:31]
	ds_read_b64 v[88:89], v162 offset:256
	ds_read_b64 v[90:91], v163 offset:256
	ds_read_b64 v[92:93], v150 offset:256
	ds_read_b64 v[94:95], v151 offset:256
	ds_read_b64 v[96:97], v152 offset:256
	ds_read_b64 v[98:99], v153 offset:256
	ds_read_b64 v[100:101], v164 offset:256
	ds_read_b64 v[102:103], v165 offset:256
	s_waitcnt lgkmcnt(8)
	v_mfma_f32_32x32x16_bf16 v[0:15], v[104:107], v[84:87], v[0:15]
	s_waitcnt lgkmcnt(6)
	v_mfma_f32_32x32x16_bf16 v[48:63], v[88:91], v[80:83], v[48:63]
	s_waitcnt lgkmcnt(4)
	v_mfma_f32_32x32x16_bf16 v[32:47], v[92:95], v[80:83], v[32:47]
	s_waitcnt lgkmcnt(2)
	v_mfma_f32_32x32x16_bf16 v[16:31], v[96:99], v[80:83], v[16:31]
	ds_read_b64 v[84:85], v154 offset:256
	ds_read_b64 v[86:87], v155 offset:256
	ds_read_b64 v[88:89], v156 offset:256
	ds_read_b64 v[90:91], v157 offset:256
	ds_read_b64 v[92:93], v187 offset:256
	ds_read_b64 v[94:95], v144 offset:256
	ds_read_b64 v[96:97], v145 offset:256
	ds_read_b64 v[98:99], v188 offset:256
	s_waitcnt lgkmcnt(8)
	v_mfma_f32_32x32x16_bf16 v[0:15], v[100:103], v[80:83], v[0:15]
	s_waitcnt lgkmcnt(6)
	v_mfma_f32_32x32x16_bf16 v[48:63], v[84:87], v[76:79], v[48:63]
	s_waitcnt lgkmcnt(4)
	v_mfma_f32_32x32x16_bf16 v[32:47], v[88:91], v[76:79], v[32:47]
	s_waitcnt lgkmcnt(2)
	v_mfma_f32_32x32x16_bf16 v[16:31], v[92:95], v[76:79], v[16:31]
	ds_read_b64 v[80:81], v146 offset:256
	ds_read_b64 v[82:83], v147 offset:256
	ds_read_b64 v[84:85], v148 offset:256
	ds_read_b64 v[86:87], v149 offset:256
	ds_read_b64 v[88:89], v189 offset:256
	ds_read_b64 v[90:91], v190 offset:256
	ds_read_b64 v[92:93], v137 offset:256
	ds_read_b64 v[94:95], v138 offset:256
	s_waitcnt lgkmcnt(8)
	v_mfma_f32_32x32x16_bf16 v[0:15], v[96:99], v[76:79], v[0:15]
	s_waitcnt lgkmcnt(6)
	v_mfma_f32_32x32x16_bf16 v[48:63], v[80:83], v[72:75], v[48:63]
	s_waitcnt lgkmcnt(4)
	v_mfma_f32_32x32x16_bf16 v[32:47], v[84:87], v[72:75], v[32:47]
	s_waitcnt lgkmcnt(2)
	v_mfma_f32_32x32x16_bf16 v[16:31], v[88:91], v[72:75], v[16:31]
	ds_read_b64 v[76:77], v140 offset:256
	ds_read_b64 v[78:79], v141 offset:256
	ds_read_b64 v[80:81], v142 offset:256
	ds_read_b64 v[82:83], v143 offset:256
	ds_read_b64 v[84:85], v191 offset:256
	ds_read_b64 v[86:87], v192 offset:256
	ds_read_b64 v[88:89], v135 offset:256
	ds_read_b64 v[90:91], v136 offset:256
	s_waitcnt lgkmcnt(8)
; DI unsigned pk2(float lo, float hi) { f32x2 v = {lo, hi}; return __builtin_bit_cast(unsigned, __builtin_convertvector(v, bf16x2v)); }
; DI void attn_prompt_item(const Params& p, int item, ldsp lds, int tid_) {
;     ...
; #pragma unroll
;     for (int dt = 0; dt < 4; ++dt)
; #pragma unroll
;       for (int g4 = 0; g4 < 4; ++g4) { u32x2 w; w.x = pk2(O[dt][4 * g4] * inv, O[dt][4 * g4 + 1] * inv); w.y = pk2(O[dt][4 * g4 + 2] * inv, O[dt][4 * g4 + 3] * inv);
;         *(u32x2*)((bf16_t*)(p.ws + B_XA) + qrow * D + h * 256 + (dh * 4 + dt) * 32 + 8 * g4 + 4 * h2) = w; }
;   }
;   __syncthreads();
; DI void phase_attn(const Params& p, ldsp lds, int tid) {
;     ...
;   for (int i = blockIdx.x; i < 256; i += G) attn_prompt_item(p, i, lds, tid);
	v_mfma_f32_32x32x16_bf16 v[0:15], v[92:95], v[72:75], v[0:15]
	s_waitcnt lgkmcnt(6)
	v_mfma_f32_32x32x16_bf16 v[48:63], v[76:79], v[68:71], v[48:63]
	s_waitcnt lgkmcnt(4)
	v_mfma_f32_32x32x16_bf16 v[32:47], v[80:83], v[68:71], v[32:47]
	s_waitcnt lgkmcnt(2)
	v_mfma_f32_32x32x16_bf16 v[16:31], v[84:87], v[68:71], v[16:31]
	ds_read_b64 v[72:73], v124 offset:256
	ds_read_b64 v[74:75], v125 offset:256
	ds_read_b64 v[76:77], v126 offset:256
	ds_read_b64 v[78:79], v127 offset:256
	ds_read_b64 v[80:81], v193 offset:256
	ds_read_b64 v[82:83], v194 offset:256
	ds_read_b64 v[84:85], v133 offset:256
	ds_read_b64 v[86:87], v134 offset:256
	s_waitcnt lgkmcnt(8)
	v_mfma_f32_32x32x16_bf16 v[0:15], v[88:91], v[68:71], v[0:15]
	s_waitcnt lgkmcnt(6)
	v_mfma_f32_32x32x16_bf16 v[48:63], v[72:75], v[64:67], v[48:63]
	s_waitcnt lgkmcnt(4)
	v_mfma_f32_32x32x16_bf16 v[32:47], v[76:79], v[64:67], v[32:47]
	s_waitcnt lgkmcnt(2)
	v_mfma_f32_32x32x16_bf16 v[16:31], v[80:83], v[64:67], v[16:31]
	s_waitcnt lgkmcnt(0)
	v_mfma_f32_32x32x16_bf16 v[0:15], v[84:87], v[64:67], v[0:15]
	s_nop 5
	v_pk_mul_f32 v[48:49], v[128:129], v[48:49] op_sel_hi:[0,1]
	v_pk_mul_f32 v[50:51], v[128:129], v[50:51] op_sel_hi:[0,1]
	v_pk_mul_f32 v[52:53], v[128:129], v[52:53] op_sel_hi:[0,1]
	v_pk_mul_f32 v[54:55], v[128:129], v[54:55] op_sel_hi:[0,1]
	v_cvt_pk_bf16_f32 v48, v48, v49
	v_cvt_pk_bf16_f32 v49, v50, v51
	v_cvt_pk_bf16_f32 v50, v52, v53
	v_cvt_pk_bf16_f32 v51, v54, v55
	v_pk_mul_f32 v[32:33], v[128:129], v[32:33] op_sel_hi:[0,1]
	v_pk_mul_f32 v[34:35], v[128:129], v[34:35] op_sel_hi:[0,1]
	v_pk_mul_f32 v[36:37], v[128:129], v[36:37] op_sel_hi:[0,1]
	v_pk_mul_f32 v[38:39], v[128:129], v[38:39] op_sel_hi:[0,1]
	v_cvt_pk_bf16_f32 v32, v32, v33
	v_cvt_pk_bf16_f32 v33, v34, v35
	v_cvt_pk_bf16_f32 v34, v36, v37
	v_cvt_pk_bf16_f32 v35, v38, v39
	v_pk_mul_f32 v[16:17], v[128:129], v[16:17] op_sel_hi:[0,1]
	v_pk_mul_f32 v[18:19], v[128:129], v[18:19] op_sel_hi:[0,1]
	v_pk_mul_f32 v[20:21], v[128:129], v[20:21] op_sel_hi:[0,1]
	v_pk_mul_f32 v[22:23], v[128:129], v[22:23] op_sel_hi:[0,1]
	v_cvt_pk_bf16_f32 v16, v16, v17
	v_cvt_pk_bf16_f32 v17, v18, v19
	v_cvt_pk_bf16_f32 v18, v20, v21
	v_cvt_pk_bf16_f32 v19, v22, v23
	v_pk_mul_f32 v[0:1], v[128:129], v[0:1] op_sel_hi:[0,1]
	v_pk_mul_f32 v[2:3], v[128:129], v[2:3] op_sel_hi:[0,1]
	v_pk_mul_f32 v[4:5], v[128:129], v[4:5] op_sel_hi:[0,1]
	v_pk_mul_f32 v[6:7], v[128:129], v[6:7] op_sel_hi:[0,1]
	v_cvt_pk_bf16_f32 v0, v0, v1
	v_cvt_pk_bf16_f32 v1, v2, v3
	v_cvt_pk_bf16_f32 v2, v4, v5
	v_cvt_pk_bf16_f32 v3, v6, v7
	s_nop 1
	v_permlane32_swap_b32_e32 v48, v50
	v_permlane32_swap_b32_e32 v49, v51
	global_store_dwordx4 v[130:131], v[48:51], off offset:256
	v_permlane32_swap_b32_e32 v32, v34
	v_permlane32_swap_b32_e32 v33, v35
	global_store_dwordx4 v[130:131], v[32:35], off offset:320
	v_permlane32_swap_b32_e32 v16, v18
	v_permlane32_swap_b32_e32 v17, v19
	global_store_dwordx4 v[130:131], v[16:19], off offset:384
	v_permlane32_swap_b32_e32 v0, v2
	v_permlane32_swap_b32_e32 v1, v3
	global_store_dwordx4 v[130:131], v[0:3], off offset:448
	v_pk_mul_f32 v[56:57], v[128:129], v[56:57] op_sel_hi:[0,1]
	v_pk_mul_f32 v[58:59], v[128:129], v[58:59] op_sel_hi:[0,1]
	v_pk_mul_f32 v[60:61], v[128:129], v[60:61] op_sel_hi:[0,1]
	v_pk_mul_f32 v[62:63], v[128:129], v[62:63] op_sel_hi:[0,1]
	v_cvt_pk_bf16_f32 v56, v56, v57
	v_cvt_pk_bf16_f32 v57, v58, v59
	v_cvt_pk_bf16_f32 v58, v60, v61
	v_cvt_pk_bf16_f32 v59, v62, v63
	v_pk_mul_f32 v[40:41], v[128:129], v[40:41] op_sel_hi:[0,1]
	v_pk_mul_f32 v[42:43], v[128:129], v[42:43] op_sel_hi:[0,1]
	v_pk_mul_f32 v[44:45], v[128:129], v[44:45] op_sel_hi:[0,1]
	v_pk_mul_f32 v[46:47], v[128:129], v[46:47] op_sel_hi:[0,1]
	v_cvt_pk_bf16_f32 v40, v40, v41
	v_cvt_pk_bf16_f32 v41, v42, v43
	v_cvt_pk_bf16_f32 v42, v44, v45
	v_cvt_pk_bf16_f32 v43, v46, v47
	v_pk_mul_f32 v[24:25], v[128:129], v[24:25] op_sel_hi:[0,1]
	v_pk_mul_f32 v[26:27], v[128:129], v[26:27] op_sel_hi:[0,1]
	v_pk_mul_f32 v[28:29], v[128:129], v[28:29] op_sel_hi:[0,1]
	v_pk_mul_f32 v[30:31], v[128:129], v[30:31] op_sel_hi:[0,1]
	v_cvt_pk_bf16_f32 v24, v24, v25
	v_cvt_pk_bf16_f32 v25, v26, v27
	v_cvt_pk_bf16_f32 v26, v28, v29
	v_cvt_pk_bf16_f32 v27, v30, v31
	v_pk_mul_f32 v[8:9], v[128:129], v[8:9] op_sel_hi:[0,1]
	v_pk_mul_f32 v[10:11], v[128:129], v[10:11] op_sel_hi:[0,1]
	v_pk_mul_f32 v[12:13], v[128:129], v[12:13] op_sel_hi:[0,1]
	v_pk_mul_f32 v[14:15], v[128:129], v[14:15] op_sel_hi:[0,1]
	v_cvt_pk_bf16_f32 v8, v8, v9
	v_cvt_pk_bf16_f32 v9, v10, v11
	v_cvt_pk_bf16_f32 v10, v12, v13
	v_cvt_pk_bf16_f32 v11, v14, v15
	s_nop 1
	s_add_i32 s45, s45, s94
	s_add_i32 s30, s30, s31
	s_add_i32 s33, s33, s34
	s_cmpk_gt_i32 s45, 0xff
	v_permlane32_swap_b32_e32 v56, v58
	v_permlane32_swap_b32_e32 v57, v59
	global_store_dwordx4 v[130:131], v[56:59], off offset:288
	v_permlane32_swap_b32_e32 v40, v42
	v_permlane32_swap_b32_e32 v41, v43
	global_store_dwordx4 v[130:131], v[40:43], off offset:352
	v_permlane32_swap_b32_e32 v24, v26
	v_permlane32_swap_b32_e32 v25, v27
	global_store_dwordx4 v[130:131], v[24:27], off offset:416
	v_permlane32_swap_b32_e32 v8, v10
	v_permlane32_swap_b32_e32 v9, v11
	global_store_dwordx4 v[130:131], v[8:11], off offset:480
	s_barrier
	s_cbranch_scc0 .LBB0_1672
